# FFN-up epilogue: the two 128-column passes now run concurrently (waves 0-1 / waves 2-3), each thread owns 8 consecutive rows x 8 columns, so conv weights are loaded once per thread and 10 source rows
# speedup vs baseline: 1.0231x; 1.0031x over previous
; #define LAS __attribute__((address_space(3)))
; DI f32x16 mfma32(bf16x8 a, bf16x8 b, f32x16 c) { return __builtin_amdgcn_mfma_f32_32x32x16_bf16(a, b, c, 0, 0, 0); }
;     ...
;   for (int kt = 0; kt < nk; ++kt) {
;     const int kn = (kt + 2 < nk) ? (kt + 2) : (nk - 1);
;     const LAS char* cur = lds + s0;
;     bf16x8 af[2][2], bfr[2][4];
; #pragma unroll
;     for (int kk = 0; kk < 2; ++kk) {
;       const int xo = kk ? x1 : x0;
;       af[kk][0] = *(const LAS bf16x8*)(cur + a_rd + xo);
;       bfr[kk][0] = *(const LAS bf16x8*)(cur + b_rd + xo);
;       bfr[kk][1] = *(const LAS bf16x8*)(cur + b_rd + 2048 + xo);
;       af[kk][1] = *(const LAS bf16x8*)(cur + a_rd + 2048 + xo);
;       bfr[kk][2] = *(const LAS bf16x8*)(cur + b_rd + 4096 + xo);
;       bfr[kk][3] = *(const LAS bf16x8*)(cur + b_rd + 6144 + xo);
;     }
;     DMA_STEP_(kn, s2);
; #pragma unroll
;     for (int kk = 0; kk < 2; ++kk) {
;       acc[0][0] = mfma32(bfr[kk][0], af[kk][0], acc[0][0]); acc[0][1] = mfma32(bfr[kk][1], af[kk][0], acc[0][1]);
;       acc[1][0] = mfma32(bfr[kk][0], af[kk][1], acc[1][0]); acc[1][1] = mfma32(bfr[kk][1], af[kk][1], acc[1][1]);
;       acc[0][2] = mfma32(bfr[kk][2], af[kk][0], acc[0][2]); acc[0][3] = mfma32(bfr[kk][3], af[kk][0], acc[0][3]);
;       acc[1][2] = mfma32(bfr[kk][2], af[kk][1], acc[1][2]); acc[1][3] = mfma32(bfr[kk][3], af[kk][1], acc[1][3]);
;     }
;     __builtin_amdgcn_sched_group_barrier(0x100, 12, 0);
;     __builtin_amdgcn_sched_group_barrier(0x010, 6, 0);
;     __builtin_amdgcn_sched_group_barrier(0x008, 16, 0);
;     asm volatile("s_waitcnt vmcnt(6) lgkmcnt(0)" ::: "memory");
;     __builtin_amdgcn_s_barrier();
;     asm volatile("" ::: "memory");
;     s0 = (s0 == 2 * STG) ? 0 : s0 + STG;
;     s2 = (s2 == 2 * STG) ? 0 : s2 + STG;
;   }
.LBB0_272:
	s_add_i32 s11, s28, 16
	s_mov_b32 s10, s21
	v_add_u32_e32 v142, s11, v218
	v_add_u32_e32 v150, s11, v0
	s_min_u32 s10, s10, 29
	v_add_u32_e32 v142, v142, v220
	v_add_u32_e32 v150, v150, v220
	s_lshl_b32 s70, s10, 6
	ds_read_b128 v[138:141], v142
	ds_read_b128 v[162:165], v150 offset:8192
	ds_read_b128 v[166:169], v150 offset:10240
	ds_read_b128 v[142:145], v142 offset:2048
	ds_read_b128 v[146:149], v150 offset:12288
	ds_read_b128 v[150:153], v150 offset:14336
	s_mul_i32 vcc_lo, s70, 0x12000
	s_add_i32 s10, s20, s23
	v_lshl_add_u64 v[222:223], v[192:193], 0, vcc
	s_mov_b32 m0, s10
	s_mul_i32 s100, s70, 0x1600
	v_lshl_add_u64 v[224:225], v[194:195], 0, s[100:101]
	s_add_i32 s10, s19, s23
	s_waitcnt lgkmcnt(6)
	v_mfma_f32_32x32x16_bf16 v[66:81], v[182:185], v[154:157], v[66:81]
	global_load_lds_dwordx4 v[222:223], off
	v_mfma_f32_32x32x16_bf16 v[82:97], v[178:181], v[154:157], v[82:97]
	global_load_lds_dwordx4 v[222:223], off offset:1024
	s_add_i32 m0, s10, 0x2000
	v_mfma_f32_32x32x16_bf16 v[18:33], v[182:185], v[158:161], v[18:33]
	global_load_lds_dwordx4 v[224:225], off
	v_mfma_f32_32x32x16_bf16 v[2:17], v[178:181], v[158:161], v[2:17]
	global_load_lds_dwordx4 v[224:225], off offset:1024
	v_mfma_f32_32x32x16_bf16 v[114:129], v[174:177], v[154:157], v[114:129]
	global_load_lds_dwordx4 v[224:225], off offset:2048
	v_mfma_f32_32x32x16_bf16 v[98:113], v[170:173], v[154:157], v[98:113]
	global_load_lds_dwordx4 v[224:225], off offset:3072
	v_mfma_f32_32x32x16_bf16 v[50:65], v[174:177], v[158:161], v[50:65]
	s_add_i32 s10, s28, 0x6000
	s_cmpk_lg_u32 s28, 0xc000
	s_cselect_b32 s28, s10, 0
	s_add_i32 s10, s23, 0x6000
	s_cmpk_lg_u32 s23, 0xc000
	s_cselect_b32 s23, s10, 0
	v_mfma_f32_32x32x16_bf16 v[34:49], v[170:173], v[158:161], v[34:49]
	s_add_i32 s11, s28, 16
	s_waitcnt vmcnt(6) lgkmcnt(0)
	s_barrier
	v_add_u32_e32 v158, s11, v218
	v_add_u32_e32 v170, s11, v0
	v_add_u32_e32 v158, v158, v219
	v_add_u32_e32 v170, v170, v219
	ds_read_b128 v[154:157], v158
	ds_read_b128 v[182:185], v170 offset:8192
	ds_read_b128 v[178:181], v170 offset:10240
	ds_read_b128 v[158:161], v158 offset:2048
	ds_read_b128 v[174:177], v170 offset:12288
	ds_read_b128 v[170:173], v170 offset:14336
	v_mfma_f32_32x32x16_bf16 v[66:81], v[162:165], v[138:141], v[66:81]
	v_mfma_f32_32x32x16_bf16 v[82:97], v[166:169], v[138:141], v[82:97]
	v_mfma_f32_32x32x16_bf16 v[18:33], v[162:165], v[142:145], v[18:33]
	v_mfma_f32_32x32x16_bf16 v[2:17], v[166:169], v[142:145], v[2:17]
	v_mfma_f32_32x32x16_bf16 v[114:129], v[146:149], v[138:141], v[114:129]
	v_mfma_f32_32x32x16_bf16 v[98:113], v[150:153], v[138:141], v[98:113]
	v_mfma_f32_32x32x16_bf16 v[50:65], v[146:149], v[142:145], v[50:65]
	v_mfma_f32_32x32x16_bf16 v[34:49], v[150:153], v[142:145], v[34:49]
	s_add_i32 s11, s28, 16
	s_add_i32 s10, s21, 1
	v_add_u32_e32 v142, s11, v218
	v_add_u32_e32 v150, s11, v0
	s_min_u32 s10, s10, 29
	v_add_u32_e32 v142, v142, v220
	v_add_u32_e32 v150, v150, v220
	s_lshl_b32 s70, s10, 6
	ds_read_b128 v[138:141], v142
	ds_read_b128 v[162:165], v150 offset:8192
	ds_read_b128 v[166:169], v150 offset:10240
	ds_read_b128 v[142:145], v142 offset:2048
	ds_read_b128 v[146:149], v150 offset:12288
	ds_read_b128 v[150:153], v150 offset:14336
	s_mul_i32 vcc_lo, s70, 0x12000
	s_add_i32 s10, s20, s23
	v_lshl_add_u64 v[222:223], v[192:193], 0, vcc
	s_mov_b32 m0, s10
	s_mul_i32 s100, s70, 0x1600
	v_lshl_add_u64 v[224:225], v[194:195], 0, s[100:101]
	s_add_i32 s10, s19, s23
	s_waitcnt lgkmcnt(6)
	v_mfma_f32_32x32x16_bf16 v[66:81], v[182:185], v[154:157], v[66:81]
	global_load_lds_dwordx4 v[222:223], off
	v_mfma_f32_32x32x16_bf16 v[82:97], v[178:181], v[154:157], v[82:97]
	global_load_lds_dwordx4 v[222:223], off offset:1024
	s_add_i32 m0, s10, 0x2000
	v_mfma_f32_32x32x16_bf16 v[18:33], v[182:185], v[158:161], v[18:33]
	global_load_lds_dwordx4 v[224:225], off
	v_mfma_f32_32x32x16_bf16 v[2:17], v[178:181], v[158:161], v[2:17]
	global_load_lds_dwordx4 v[224:225], off offset:1024
	v_mfma_f32_32x32x16_bf16 v[114:129], v[174:177], v[154:157], v[114:129]
	global_load_lds_dwordx4 v[224:225], off offset:2048
	v_mfma_f32_32x32x16_bf16 v[98:113], v[170:173], v[154:157], v[98:113]
	global_load_lds_dwordx4 v[224:225], off offset:3072
	v_mfma_f32_32x32x16_bf16 v[50:65], v[174:177], v[158:161], v[50:65]
	s_add_i32 s10, s28, 0x6000
	s_cmpk_lg_u32 s28, 0xc000
	s_cselect_b32 s28, s10, 0
	s_add_i32 s10, s23, 0x6000
	s_cmpk_lg_u32 s23, 0xc000
	s_cselect_b32 s23, s10, 0
	v_mfma_f32_32x32x16_bf16 v[34:49], v[170:173], v[158:161], v[34:49]
	s_add_i32 s11, s28, 16
	s_waitcnt vmcnt(6) lgkmcnt(0)
	s_barrier
	v_add_u32_e32 v158, s11, v218
	v_add_u32_e32 v170, s11, v0
	v_add_u32_e32 v158, v158, v219
	v_add_u32_e32 v170, v170, v219
	ds_read_b128 v[154:157], v158
	ds_read_b128 v[182:185], v170 offset:8192
	ds_read_b128 v[178:181], v170 offset:10240
	ds_read_b128 v[158:161], v158 offset:2048
	ds_read_b128 v[174:177], v170 offset:12288
	ds_read_b128 v[170:173], v170 offset:14336
	v_mfma_f32_32x32x16_bf16 v[66:81], v[162:165], v[138:141], v[66:81]
	v_mfma_f32_32x32x16_bf16 v[82:97], v[166:169], v[138:141], v[82:97]
	v_mfma_f32_32x32x16_bf16 v[18:33], v[162:165], v[142:145], v[18:33]
	v_mfma_f32_32x32x16_bf16 v[2:17], v[166:169], v[142:145], v[2:17]
	v_mfma_f32_32x32x16_bf16 v[114:129], v[146:149], v[138:141], v[114:129]
	v_mfma_f32_32x32x16_bf16 v[98:113], v[150:153], v[138:141], v[98:113]
	v_mfma_f32_32x32x16_bf16 v[50:65], v[146:149], v[142:145], v[50:65]
	v_mfma_f32_32x32x16_bf16 v[34:49], v[150:153], v[142:145], v[34:49]
	s_add_i32 s21, s21, 2
	s_cmp_eq_u32 s21, 30
	s_cbranch_scc0 .LBB0_272
; #define LAS __attribute__((address_space(3)))
; DI unsigned pk2(float a, float b) { f32x2 v = {a, b}; bf2_t r = __builtin_convertvector(v, bf2_t); return __builtin_bit_cast(unsigned, r); }
; DI f32x16 mfma32(bf16x8 a, bf16x8 b, f32x16 c) { return __builtin_amdgcn_mfma_f32_32x32x16_bf16(a, b, c, 0, 0, 0); }
;     ...
;     for (int kk = 0; kk < 2; ++kk) {
;       const int xo = kk ? x1 : x0;
;       af[kk][0] = *(const LAS bf16x8*)(cur + a_rd + xo);
;       bfr[kk][0] = *(const LAS bf16x8*)(cur + b_rd + xo);
;       bfr[kk][1] = *(const LAS bf16x8*)(cur + b_rd + 2048 + xo);
;       af[kk][1] = *(const LAS bf16x8*)(cur + a_rd + 2048 + xo);
;       bfr[kk][2] = *(const LAS bf16x8*)(cur + b_rd + 4096 + xo);
;       bfr[kk][3] = *(const LAS bf16x8*)(cur + b_rd + 6144 + xo);
;     }
;     DMA_STEP_(kn, s2);
; #pragma unroll
;     for (int kk = 0; kk < 2; ++kk) {
;       acc[0][0] = mfma32(bfr[kk][0], af[kk][0], acc[0][0]); acc[0][1] = mfma32(bfr[kk][1], af[kk][0], acc[0][1]);
;       acc[1][0] = mfma32(bfr[kk][0], af[kk][1], acc[1][0]); acc[1][1] = mfma32(bfr[kk][1], af[kk][1], acc[1][1]);
;       acc[0][2] = mfma32(bfr[kk][2], af[kk][0], acc[0][2]); acc[0][3] = mfma32(bfr[kk][3], af[kk][0], acc[0][3]);
;       acc[1][2] = mfma32(bfr[kk][2], af[kk][1], acc[1][2]); acc[1][3] = mfma32(bfr[kk][3], af[kk][1], acc[1][3]);
;     }
;     __builtin_amdgcn_sched_group_barrier(0x100, 12, 0);
;     __builtin_amdgcn_sched_group_barrier(0x010, 6, 0);
;     __builtin_amdgcn_sched_group_barrier(0x008, 16, 0);
;     asm volatile("s_waitcnt vmcnt(6) lgkmcnt(0)" ::: "memory");
;     __builtin_amdgcn_s_barrier();
;     asm volatile("" ::: "memory");
;     s0 = (s0 == 2 * STG) ? 0 : s0 + STG;
;     s2 = (s2 == 2 * STG) ? 0 : s2 + STG;
;   }
;   asm volatile("s_waitcnt vmcnt(0)" ::: "memory");
;   __builtin_amdgcn_s_barrier();
;   asm volatile("" ::: "memory");
;     ...
;   {
;     const int h = lane >> 5, cl = lane & 31;
; #pragma unroll
;     for (int i = 0; i < 2; ++i)
; #pragma unroll
;       for (int j = 0; j < 4; ++j)
; #pragma unroll
;         for (int g = 0; g < 4; ++g) {
;           u32x2 w; w.x = pk2(acc[i][j][4 * g], acc[i][j][4 * g + 1]); w.y = pk2(acc[i][j][4 * g + 2], acc[i][j][4 * g + 3]);
;           *(u32x2*)(smem + (wr * 64 + i * 32 + cl) * 528 + (wc * 128 + j * 32 + 8 * g + 4 * h) * 2) = w;
;         }
	s_add_i32 s11, s28, 16
	v_add_u32_e32 v142, s11, v218
	v_add_u32_e32 v150, s11, v0
	v_add_u32_e32 v142, v142, v220
	v_add_u32_e32 v150, v150, v220
	ds_read_b128 v[138:141], v142
	ds_read_b128 v[162:165], v150 offset:8192
	ds_read_b128 v[166:169], v150 offset:10240
	ds_read_b128 v[142:145], v142 offset:2048
	ds_read_b128 v[146:149], v150 offset:12288
	ds_read_b128 v[150:153], v150 offset:14336
	s_waitcnt lgkmcnt(6)
	v_mfma_f32_32x32x16_bf16 v[66:81], v[182:185], v[154:157], v[66:81]
	v_mfma_f32_32x32x16_bf16 v[82:97], v[178:181], v[154:157], v[82:97]
	v_mfma_f32_32x32x16_bf16 v[18:33], v[182:185], v[158:161], v[18:33]
	v_mfma_f32_32x32x16_bf16 v[2:17], v[178:181], v[158:161], v[2:17]
	v_mfma_f32_32x32x16_bf16 v[114:129], v[174:177], v[154:157], v[114:129]
	v_mfma_f32_32x32x16_bf16 v[98:113], v[170:173], v[154:157], v[98:113]
	v_mfma_f32_32x32x16_bf16 v[50:65], v[174:177], v[158:161], v[50:65]
	s_add_i32 s10, s28, 0x6000
	s_cmpk_lg_u32 s28, 0xc000
	s_cselect_b32 s28, s10, 0
	v_mfma_f32_32x32x16_bf16 v[34:49], v[170:173], v[158:161], v[34:49]
	s_add_i32 s11, s28, 16
	s_waitcnt vmcnt(0) lgkmcnt(0)
	s_barrier
	v_add_u32_e32 v158, s11, v218
	v_add_u32_e32 v170, s11, v0
	v_add_u32_e32 v158, v158, v219
	v_add_u32_e32 v170, v170, v219
	ds_read_b128 v[154:157], v158
	ds_read_b128 v[182:185], v170 offset:8192
	ds_read_b128 v[178:181], v170 offset:10240
	ds_read_b128 v[158:161], v158 offset:2048
	ds_read_b128 v[174:177], v170 offset:12288
	ds_read_b128 v[170:173], v170 offset:14336
	v_mfma_f32_32x32x16_bf16 v[66:81], v[162:165], v[138:141], v[66:81]
	v_mfma_f32_32x32x16_bf16 v[82:97], v[166:169], v[138:141], v[82:97]
	v_mfma_f32_32x32x16_bf16 v[18:33], v[162:165], v[142:145], v[18:33]
	v_mfma_f32_32x32x16_bf16 v[2:17], v[166:169], v[142:145], v[2:17]
	v_mfma_f32_32x32x16_bf16 v[114:129], v[146:149], v[138:141], v[114:129]
	v_mfma_f32_32x32x16_bf16 v[98:113], v[150:153], v[138:141], v[98:113]
	v_mfma_f32_32x32x16_bf16 v[50:65], v[146:149], v[142:145], v[50:65]
	v_mfma_f32_32x32x16_bf16 v[34:49], v[150:153], v[142:145], v[34:49]
	s_add_i32 s11, s28, 16
	v_add_u32_e32 v142, s11, v218
	v_add_u32_e32 v150, s11, v0
	v_add_u32_e32 v142, v142, v220
	v_add_u32_e32 v150, v150, v220
	ds_read_b128 v[138:141], v142
	ds_read_b128 v[162:165], v150 offset:8192
	ds_read_b128 v[166:169], v150 offset:10240
	ds_read_b128 v[142:145], v142 offset:2048
	ds_read_b128 v[146:149], v150 offset:12288
	ds_read_b128 v[150:153], v150 offset:14336
	s_waitcnt lgkmcnt(6)
	v_mfma_f32_32x32x16_bf16 v[66:81], v[182:185], v[154:157], v[66:81]
	v_mfma_f32_32x32x16_bf16 v[82:97], v[178:181], v[154:157], v[82:97]
	v_mfma_f32_32x32x16_bf16 v[18:33], v[182:185], v[158:161], v[18:33]
	v_mfma_f32_32x32x16_bf16 v[2:17], v[178:181], v[158:161], v[2:17]
	v_mfma_f32_32x32x16_bf16 v[114:129], v[174:177], v[154:157], v[114:129]
	v_mfma_f32_32x32x16_bf16 v[98:113], v[170:173], v[154:157], v[98:113]
	v_mfma_f32_32x32x16_bf16 v[50:65], v[174:177], v[158:161], v[50:65]
	v_mfma_f32_32x32x16_bf16 v[34:49], v[170:173], v[158:161], v[34:49]
	s_waitcnt lgkmcnt(0)
	v_mfma_f32_32x32x16_bf16 v[66:81], v[162:165], v[138:141], v[66:81]
	v_mfma_f32_32x32x16_bf16 v[82:97], v[166:169], v[138:141], v[82:97]
	v_mfma_f32_32x32x16_bf16 v[18:33], v[162:165], v[142:145], v[18:33]
	v_mfma_f32_32x32x16_bf16 v[2:17], v[166:169], v[142:145], v[2:17]
	v_mfma_f32_32x32x16_bf16 v[114:129], v[146:149], v[138:141], v[114:129]
	v_mfma_f32_32x32x16_bf16 v[98:113], v[150:153], v[138:141], v[98:113]
	v_mfma_f32_32x32x16_bf16 v[50:65], v[146:149], v[142:145], v[50:65]
	v_mfma_f32_32x32x16_bf16 v[34:49], v[150:153], v[142:145], v[34:49]
	s_waitcnt lgkmcnt(0)
	s_setprio 0
	v_mul_lo_u32 v0, v197, s55
	v_add_u32_e32 v0, 16, v0
	s_nop 1
	v_cvt_pk_bf16_f32 v66, v66, v67
	v_cvt_pk_bf16_f32 v67, v68, v69
	v_lshlrev_b32_e32 v68, 3, v196
	s_lshl_b32 s10, s18, 1
	v_add3_u32 v0, v0, v68, s10
	v_cvt_pk_bf16_f32 v68, v70, v71
	v_cvt_pk_bf16_f32 v69, v72, v73
	s_waitcnt vmcnt(0)
	s_barrier
; #define GAS __attribute__((address_space(1)))
; DI unsigned pk2(float a, float b) { f32x2 v = {a, b}; bf2_t r = __builtin_convertvector(v, bf2_t); return __builtin_bit_cast(unsigned, r); }
;     ...
; #pragma unroll
;     for (int i = 0; i < 2; ++i)
; #pragma unroll
;       for (int j = 0; j < 4; ++j)
; #pragma unroll
;         for (int g = 0; g < 4; ++g) {
;           u32x2 w; w.x = pk2(acc[i][j][4 * g], acc[i][j][4 * g + 1]); w.y = pk2(acc[i][j][4 * g + 2], acc[i][j][4 * g + 3]);
;           *(u32x2*)(smem + (wr * 64 + i * 32 + cl) * 528 + (wc * 128 + j * 32 + 8 * g + 4 * h) * 2) = w;
;         }
;   }
;   __syncthreads();
;   int tid2 = tid; asm volatile("" : "+v"(tid2));
;   if (EPI == 0) {
; #pragma unroll
;     for (int i = 0; i < 16; ++i) {
;       const int id = tid2 + 256 * i, r = id >> 5, c8 = (id & 31) * 8;
;       const u32x4 v = *(const u32x4*)(smem + r * 528 + c8 * 2);
;       *(GAS u32x4*)(ea.out + (size_t)(m0 + r) * ea.ldo + n0 + c8) = v;
;     }
;   } else {
;     const int L = (mt < 512) ? 2048 : 256;
;     const bool first = (m0 % L) == 0, last = ((m0 + 128) % L) == 0;
;     const float* cw = ea.cw; const float* cb = ea.cb;
; #pragma unroll 1
;     for (int p = 0; p < 2; ++p) {
;       const int j8 = (tid2 & 7) * 8;
;       const int ja0 = (nt * 2 + p) * 64, ja = ja0 + j8;
	ds_write2_b64 v0, v[66:67], v[68:69] offset1:2
	v_cvt_pk_bf16_f32 v66, v74, v75
	v_cvt_pk_bf16_f32 v67, v76, v77
	v_cvt_pk_bf16_f32 v68, v78, v79
	v_cvt_pk_bf16_f32 v69, v80, v81
	ds_write2_b64 v0, v[66:67], v[68:69] offset0:4 offset1:6
	v_cvt_pk_bf16_f32 v66, v82, v83
	v_cvt_pk_bf16_f32 v67, v84, v85
	v_cvt_pk_bf16_f32 v68, v86, v87
	v_cvt_pk_bf16_f32 v69, v88, v89
	ds_write2_b64 v0, v[66:67], v[68:69] offset0:8 offset1:10
	v_cvt_pk_bf16_f32 v66, v90, v91
	v_cvt_pk_bf16_f32 v67, v92, v93
	v_cvt_pk_bf16_f32 v68, v94, v95
	v_cvt_pk_bf16_f32 v69, v96, v97
	ds_write2_b64 v0, v[66:67], v[68:69] offset0:12 offset1:14
	v_cvt_pk_bf16_f32 v66, v114, v115
	v_cvt_pk_bf16_f32 v67, v116, v117
	v_cvt_pk_bf16_f32 v68, v118, v119
	v_cvt_pk_bf16_f32 v69, v120, v121
	ds_write2_b64 v0, v[66:67], v[68:69] offset0:16 offset1:18
	v_cvt_pk_bf16_f32 v66, v122, v123
	v_cvt_pk_bf16_f32 v67, v124, v125
	v_cvt_pk_bf16_f32 v68, v126, v127
	v_cvt_pk_bf16_f32 v69, v128, v129
	ds_write2_b64 v0, v[66:67], v[68:69] offset0:20 offset1:22
	v_cvt_pk_bf16_f32 v66, v98, v99
	v_cvt_pk_bf16_f32 v67, v100, v101
	v_cvt_pk_bf16_f32 v68, v102, v103
	v_cvt_pk_bf16_f32 v69, v104, v105
	ds_write2_b64 v0, v[66:67], v[68:69] offset0:24 offset1:26
	v_cvt_pk_bf16_f32 v66, v106, v107
	v_cvt_pk_bf16_f32 v67, v108, v109
	v_cvt_pk_bf16_f32 v68, v110, v111
	v_cvt_pk_bf16_f32 v69, v112, v113
	ds_write2_b64 v0, v[66:67], v[68:69] offset0:28 offset1:30
	v_add_u32_e32 v0, 0x4000, v0
	v_cvt_pk_bf16_f32 v2, v2, v3
	v_cvt_pk_bf16_f32 v3, v4, v5
	v_cvt_pk_bf16_f32 v4, v6, v7
	v_cvt_pk_bf16_f32 v5, v8, v9
	ds_write2_b64 v0, v[2:3], v[4:5] offset0:72 offset1:74
	v_cvt_pk_bf16_f32 v2, v10, v11
	v_cvt_pk_bf16_f32 v3, v12, v13
	v_cvt_pk_bf16_f32 v4, v14, v15
	v_cvt_pk_bf16_f32 v5, v16, v17
	ds_write2_b64 v0, v[2:3], v[4:5] offset0:76 offset1:78
	v_cvt_pk_bf16_f32 v2, v50, v51
	v_cvt_pk_bf16_f32 v3, v52, v53
	v_cvt_pk_bf16_f32 v4, v54, v55
	v_cvt_pk_bf16_f32 v5, v56, v57
	s_cmpk_lt_i32 s15, 0x200
	ds_write2_b64 v0, v[2:3], v[4:5] offset0:80 offset1:82
	v_cvt_pk_bf16_f32 v2, v58, v59
	v_cvt_pk_bf16_f32 v3, v60, v61
	v_cvt_pk_bf16_f32 v4, v62, v63
	v_cvt_pk_bf16_f32 v5, v64, v65
	s_cselect_b32 s10, 0x7ff, s78
	v_cvt_pk_bf16_f32 v18, v18, v19
	v_cvt_pk_bf16_f32 v19, v20, v21
	v_cvt_pk_bf16_f32 v20, v22, v23
	v_cvt_pk_bf16_f32 v21, v24, v25
	ds_write2_b64 v0, v[2:3], v[4:5] offset0:84 offset1:86
	v_cvt_pk_bf16_f32 v2, v34, v35
	v_cvt_pk_bf16_f32 v3, v36, v37
	v_cvt_pk_bf16_f32 v4, v38, v39
	v_cvt_pk_bf16_f32 v5, v40, v41
	s_and_b32 s11, s10, s46
	ds_write2_b64 v0, v[18:19], v[20:21] offset0:64 offset1:66
	v_cvt_pk_bf16_f32 v18, v26, v27
	v_cvt_pk_bf16_f32 v19, v28, v29
	v_cvt_pk_bf16_f32 v20, v30, v31
	v_cvt_pk_bf16_f32 v21, v32, v33
	ds_write2_b64 v0, v[2:3], v[4:5] offset0:88 offset1:90
	v_cvt_pk_bf16_f32 v2, v42, v43
	v_cvt_pk_bf16_f32 v3, v44, v45
	v_cvt_pk_bf16_f32 v4, v46, v47
	v_cvt_pk_bf16_f32 v5, v48, v49
	s_cmp_eq_u32 s11, 0
	ds_write2_b64 v0, v[18:19], v[20:21] offset0:68 offset1:70
	ds_write2_b64 v0, v[2:3], v[4:5] offset0:92 offset1:94
	s_waitcnt vmcnt(0) lgkmcnt(0)
	s_barrier
	s_cselect_b64 s[18:19], -1, 0
	s_add_i32 s11, s46, 0x80
	v_lshlrev_b32_e32 v0, 3, v189
	s_and_b32 s10, s11, s10
	v_and_b32_e32 v96, 56, v0
	s_cmp_eq_u32 s10, 0
	v_lshlrev_b32_e32 v0, 1, v96
	v_lshrrev_b32_e32 v98, 7, v189
	s_nop 0
	v_readfirstlane_b32 s40, v98
	s_cselect_b64 s[20:21], -1, 0
	s_lshl_b32 s47, s22, 7
	v_add_u32_e32 v97, 16, v0
	v_lshl_add_u64 v[90:91], s[44:45], 0, v[0:1]
	s_mov_b64 s[28:29], 0
	s_branch .LBB0_275

; #define GAS __attribute__((address_space(1)))
; DI float bflo(unsigned w) { return __uint_as_float(w << 16); }
;     ...
;       const int j8 = (tid2 & 7) * 8;
;       const int ja0 = (nt * 2 + p) * 64, ja = ja0 + j8;
;       f32x4 wa[4][2], wg[4][2];
; #pragma unroll
;       for (int hh = 0; hh < 2; ++hh) {
;         wa[0][hh] = *(const GAS f32x4*)(cw + ja + 4 * hh); wa[1][hh] = *(const GAS f32x4*)(cw + 5632 + ja + 4 * hh); wa[2][hh] = *(const GAS f32x4*)(cw + 11264 + ja + 4 * hh); wa[3][hh] = *(const GAS f32x4*)(cb + ja + 4 * hh);
;         wg[0][hh] = *(const GAS f32x4*)(cw + 2816 + ja + 4 * hh); wg[1][hh] = *(const GAS f32x4*)(cw + 5632 + 2816 + ja + 4 * hh); wg[2][hh] = *(const GAS f32x4*)(cw + 11264 + 2816 + ja + 4 * hh); wg[3][hh] = *(const GAS f32x4*)(cb + 2816 + ja + 4 * hh);
;       }
; #pragma unroll 1
;       for (int i = 0; i < 4; ++i) {
;         const int r = (tid2 + 256 * i) >> 3;
;         const bool top = (r == 0), bot = (r == 127);
;         if ((top && !first) || (bot && !last)) continue;
;         const char* base = smem + r * 528 + (p * 128 + j8) * 2;
;         const u32x4 zz = {0u, 0u, 0u, 0u};
;         const u32x4 pa = top ? zz : *(const u32x4*)(base - 528), ca = *(const u32x4*)base, na = bot ? zz : *(const u32x4*)(base + 528);
;         const u32x4 pg = top ? zz : *(const u32x4*)(base - 528 + 128), cg = *(const u32x4*)(base + 128), ng = bot ? zz : *(const u32x4*)(base + 528 + 128);
;         unsigned resw[4];
; #pragma unroll
;         for (int q = 0; q < 4; ++q) {
;           const int hh = q >> 1, e0 = (q & 1) * 2;
;           const float ua0 = wa[0][hh][e0] * bflo(pa[q]) + wa[1][hh][e0] * bflo(ca[q]) + wa[2][hh][e0] * bflo(na[q]) + wa[3][hh][e0];
;           const float ua1 = wa[0][hh][e0 + 1] * bfhi(pa[q]) + wa[1][hh][e0 + 1] * bfhi(ca[q]) + wa[2][hh][e0 + 1] * bfhi(na[q]) + wa[3][hh][e0 + 1];
;           const float ug0 = wg[0][hh][e0] * bflo(pg[q]) + wg[1][hh][e0] * bflo(cg[q]) + wg[2][hh][e0] * bflo(ng[q]) + wg[3][hh][e0];
;           const float ug1 = wg[0][hh][e0 + 1] * bfhi(pg[q]) + wg[1][hh][e0 + 1] * bfhi(cg[q]) + wg[2][hh][e0 + 1] * bfhi(ng[q]) + wg[3][hh][e0 + 1];
;           resw[q] = pk2(siluf(ug0) * ua0, siluf(ug1) * ua1);
;         }
;         u32x4 w; w.x = resw[0]; w.y = resw[1]; w.z = resw[2]; w.w = resw[3];
;         __builtin_nontemporal_store(w, (GAS u32x4*)(ea.out + (size_t)(m0 + r) * 2816 + ja0 + j8));
.LBB0_278:
	v_bfe_u32 v98, v189, 3, 4
	v_lshlrev_b32_e32 v98, 3, v98
	v_mad_u64_u32 v[94:95], s[74:75], v98, s55, v[0:1]
	v_cmp_ne_u32_e32 vcc, 0, v98
	v_add_u32_e32 v99, 0xfffffdf0, v94
	s_movk_i32 s10, 0x78
	v_cmp_eq_u32_e64 s[74:75], 0, v98
	v_cndmask_b32_e32 v99, v94, v99, vcc
	v_cmp_eq_u32_e64 s[40:41], s10, v98
	ds_read_b128 v[138:141], v99
	ds_read_b128 v[142:145], v99 offset:128
	ds_read_b128 v[146:149], v94 offset:0
	ds_read_b128 v[150:153], v94 offset:128
	ds_read_b128 v[154:157], v94 offset:528
	ds_read_b128 v[158:161], v94 offset:656
	ds_read_b128 v[162:165], v94 offset:1056
	ds_read_b128 v[166:169], v94 offset:1184
	ds_read_b128 v[170:173], v94 offset:1584
	ds_read_b128 v[174:177], v94 offset:1712
	ds_read_b128 v[178:181], v94 offset:2112
	ds_read_b128 v[182:185], v94 offset:2240
	v_add_u32_e32 v88, s46, v98
	s_movk_i32 s10, 0x1600
	v_mad_i64_i32 v[88:89], s[28:29], v88, s10, v[92:93]
	s_mov_b32 s11, 0
	s_waitcnt vmcnt(0)
	s_waitcnt lgkmcnt(10)
	s_and_b64 s[28:29], exec, s[74:75]
	s_cbranch_scc0 .Lmy_e1_top
	s_mov_b64 vcc, exec
	s_mov_b64 exec, s[28:29]
	v_mov_b32_e32 v138, 0
	v_mov_b32_e32 v139, 0
	v_mov_b32_e32 v140, 0
	v_mov_b32_e32 v141, 0
	v_mov_b32_e32 v142, 0
	v_mov_b32_e32 v143, 0
	v_mov_b32_e32 v144, 0
	v_mov_b32_e32 v145, 0
	s_mov_b64 exec, vcc
.Lmy_e1_top:
	v_lshlrev_b32_e32 v66, 16, v138
	v_and_b32_e32 v67, 0xffff0000, v138
	v_lshlrev_b32_e32 v68, 16, v139
	v_and_b32_e32 v69, 0xffff0000, v139
	v_lshlrev_b32_e32 v70, 16, v140
	v_and_b32_e32 v71, 0xffff0000, v140
	v_lshlrev_b32_e32 v72, 16, v141
	v_and_b32_e32 v73, 0xffff0000, v141
	v_lshlrev_b32_e32 v74, 16, v142
	v_and_b32_e32 v75, 0xffff0000, v142
	v_lshlrev_b32_e32 v76, 16, v143
	v_and_b32_e32 v77, 0xffff0000, v143
	v_lshlrev_b32_e32 v78, 16, v144
	v_and_b32_e32 v79, 0xffff0000, v144
	v_lshlrev_b32_e32 v80, 16, v145
	v_and_b32_e32 v81, 0xffff0000, v145
	s_waitcnt lgkmcnt(8)
	v_lshlrev_b32_e32 v104, 16, v146
	v_and_b32_e32 v105, 0xffff0000, v146
	v_lshlrev_b32_e32 v106, 16, v147
	v_and_b32_e32 v107, 0xffff0000, v147
	v_lshlrev_b32_e32 v108, 16, v148
	v_and_b32_e32 v109, 0xffff0000, v148
	v_lshlrev_b32_e32 v110, 16, v149
	v_and_b32_e32 v111, 0xffff0000, v149
	v_lshlrev_b32_e32 v112, 16, v150
	v_and_b32_e32 v113, 0xffff0000, v150
	v_lshlrev_b32_e32 v114, 16, v151
	v_and_b32_e32 v115, 0xffff0000, v151
	v_lshlrev_b32_e32 v116, 16, v152
	v_and_b32_e32 v117, 0xffff0000, v152
	v_lshlrev_b32_e32 v118, 16, v153
	v_and_b32_e32 v119, 0xffff0000, v153
	s_waitcnt lgkmcnt(6)
	v_lshlrev_b32_e32 v120, 16, v154
	v_and_b32_e32 v121, 0xffff0000, v154
	v_lshlrev_b32_e32 v122, 16, v155
	v_and_b32_e32 v123, 0xffff0000, v155
	v_lshlrev_b32_e32 v124, 16, v156
	v_and_b32_e32 v125, 0xffff0000, v156
	v_lshlrev_b32_e32 v126, 16, v157
	v_and_b32_e32 v127, 0xffff0000, v157
	v_lshlrev_b32_e32 v128, 16, v158
	v_and_b32_e32 v129, 0xffff0000, v158
	v_lshlrev_b32_e32 v82, 16, v159
	v_and_b32_e32 v83, 0xffff0000, v159
	v_lshlrev_b32_e32 v84, 16, v160
	v_and_b32_e32 v85, 0xffff0000, v160
	v_lshlrev_b32_e32 v86, 16, v161
	v_and_b32_e32 v87, 0xffff0000, v161
	v_mul_f32_e32 v138, v10, v104
	v_mul_f32_e32 v139, v11, v105
	v_mul_f32_e32 v140, v12, v106
	v_mul_f32_e32 v141, v13, v107
	v_fma_f32 v66, v2, v66, v138
	v_fma_f32 v67, v3, v67, v139
	v_fma_f32 v68, v4, v68, v140
	v_fma_f32 v69, v5, v69, v141
	v_fma_f32 v66, v18, v120, v66
	v_fma_f32 v67, v19, v121, v67
	v_fma_f32 v68, v20, v122, v68
	v_fma_f32 v69, v21, v123, v69
	v_add_f32_e32 v66, v26, v66
	v_add_f32_e32 v67, v27, v67
	v_add_f32_e32 v68, v28, v68
	v_add_f32_e32 v69, v29, v69
	v_mul_f32_e32 v138, v14, v108
	v_mul_f32_e32 v139, v15, v109
	v_mul_f32_e32 v140, v16, v110
	v_mul_f32_e32 v141, v17, v111
	v_fma_f32 v70, v6, v70, v138
	v_fma_f32 v71, v7, v71, v139
	v_fma_f32 v72, v8, v72, v140
	v_fma_f32 v73, v9, v73, v141
	v_fma_f32 v70, v22, v124, v70
	v_fma_f32 v71, v23, v125, v71
	v_fma_f32 v72, v24, v126, v72
	v_fma_f32 v73, v25, v127, v73
	v_add_f32_e32 v70, v30, v70
	v_add_f32_e32 v71, v31, v71
	v_add_f32_e32 v72, v32, v72
	v_add_f32_e32 v73, v33, v73
	v_mul_f32_e32 v142, v42, v112
	v_mul_f32_e32 v143, v43, v113
	v_mul_f32_e32 v144, v44, v114
	v_mul_f32_e32 v145, v45, v115
	v_fma_f32 v74, v34, v74, v142
	v_fma_f32 v75, v35, v75, v143
	v_fma_f32 v76, v36, v76, v144
	v_fma_f32 v77, v37, v77, v145
	v_fma_f32 v74, v50, v128, v74
	v_fma_f32 v75, v51, v129, v75
	v_fma_f32 v76, v52, v82, v76
	v_fma_f32 v77, v53, v83, v77
	v_add_f32_e32 v74, v58, v74
	v_add_f32_e32 v75, v59, v75
	v_add_f32_e32 v76, v60, v76
	v_add_f32_e32 v77, v61, v77
	v_mul_f32_e32 v142, v46, v116
	v_mul_f32_e32 v143, v47, v117
	v_mul_f32_e32 v144, v48, v118
	v_mul_f32_e32 v145, v49, v119
	v_fma_f32 v78, v38, v78, v142
	v_fma_f32 v79, v39, v79, v143
	v_fma_f32 v80, v40, v80, v144
	v_fma_f32 v81, v41, v81, v145
	v_fma_f32 v78, v54, v84, v78
	v_fma_f32 v79, v55, v85, v79
	v_fma_f32 v80, v56, v86, v80
	v_fma_f32 v81, v57, v87, v81
	v_add_f32_e32 v78, v62, v78
	v_add_f32_e32 v79, v63, v79
	v_add_f32_e32 v80, v64, v80
	v_add_f32_e32 v81, v65, v81
	v_mul_f32_e32 v138, 0xbfb8aa3b, v74
	v_mul_f32_e32 v139, 0xbfb8aa3b, v75
	v_mul_f32_e32 v140, 0xbfb8aa3b, v76
	v_mul_f32_e32 v141, 0xbfb8aa3b, v77
	v_exp_f32_e32 v138, v138
	v_exp_f32_e32 v139, v139
	v_exp_f32_e32 v140, v140
	v_exp_f32_e32 v141, v141
	v_add_f32_e32 v138, 1.0, v138
	v_add_f32_e32 v139, 1.0, v139
	v_add_f32_e32 v140, 1.0, v140
	v_add_f32_e32 v141, 1.0, v141
	v_rcp_f32_e32 v138, v138
	v_rcp_f32_e32 v139, v139
	v_rcp_f32_e32 v140, v140
	v_rcp_f32_e32 v141, v141
	v_mul_f32_e32 v74, v74, v138
	v_mul_f32_e32 v75, v75, v139
	v_mul_f32_e32 v76, v76, v140
	v_mul_f32_e32 v77, v77, v141
	v_mul_f32_e32 v66, v66, v74
	v_mul_f32_e32 v67, v67, v75
	v_mul_f32_e32 v68, v68, v76
	v_mul_f32_e32 v69, v69, v77
	v_mul_f32_e32 v138, 0xbfb8aa3b, v78
	v_mul_f32_e32 v139, 0xbfb8aa3b, v79
	v_mul_f32_e32 v140, 0xbfb8aa3b, v80
	v_mul_f32_e32 v141, 0xbfb8aa3b, v81
	v_exp_f32_e32 v138, v138
	v_exp_f32_e32 v139, v139
	v_exp_f32_e32 v140, v140
	v_exp_f32_e32 v141, v141
	v_add_f32_e32 v138, 1.0, v138
	v_add_f32_e32 v139, 1.0, v139
	v_add_f32_e32 v140, 1.0, v140
	v_add_f32_e32 v141, 1.0, v141
	v_rcp_f32_e32 v138, v138
	v_rcp_f32_e32 v139, v139
	v_rcp_f32_e32 v140, v140
	v_rcp_f32_e32 v141, v141
	v_mul_f32_e32 v78, v78, v138
	v_mul_f32_e32 v79, v79, v139
	v_mul_f32_e32 v80, v80, v140
	v_mul_f32_e32 v81, v81, v141
	v_mul_f32_e32 v70, v70, v78
	v_mul_f32_e32 v71, v71, v79
	v_mul_f32_e32 v72, v72, v80
	v_mul_f32_e32 v73, v73, v81
	v_cvt_pk_bf16_f32 v100, v66, v67
	v_cvt_pk_bf16_f32 v101, v68, v69
	v_cvt_pk_bf16_f32 v102, v70, v71
	v_cvt_pk_bf16_f32 v103, v72, v73
	s_mov_b64 vcc, exec
	s_orn2_b64 s[28:29], s[18:19], s[74:75]
	s_and_b64 exec, exec, s[28:29]
	global_store_dwordx4 v[88:89], v[100:103], off nt
	s_mov_b64 exec, vcc
	v_lshl_add_u64 v[88:89], v[88:89], 0, s[10:11]
	s_waitcnt lgkmcnt(4)
; #define GAS __attribute__((address_space(1)))
; DI unsigned pk2(float a, float b) { f32x2 v = {a, b}; bf2_t r = __builtin_convertvector(v, bf2_t); return __builtin_bit_cast(unsigned, r); }
; DI float bflo(unsigned w) { return __uint_as_float(w << 16); }
; DI float bfhi(unsigned w) { return __uint_as_float(w & 0xffff0000u); }
; DI float siluf(float v) { return v * __builtin_amdgcn_rcpf(1.f + __builtin_amdgcn_exp2f(-1.4426950408889634f * v)); }
;     ...
;         for (int q = 0; q < 4; ++q) {
;           const int hh = q >> 1, e0 = (q & 1) * 2;
;           const float ua0 = wa[0][hh][e0] * bflo(pa[q]) + wa[1][hh][e0] * bflo(ca[q]) + wa[2][hh][e0] * bflo(na[q]) + wa[3][hh][e0];
;           const float ua1 = wa[0][hh][e0 + 1] * bfhi(pa[q]) + wa[1][hh][e0 + 1] * bfhi(ca[q]) + wa[2][hh][e0 + 1] * bfhi(na[q]) + wa[3][hh][e0 + 1];
;           const float ug0 = wg[0][hh][e0] * bflo(pg[q]) + wg[1][hh][e0] * bflo(cg[q]) + wg[2][hh][e0] * bflo(ng[q]) + wg[3][hh][e0];
;           const float ug1 = wg[0][hh][e0 + 1] * bfhi(pg[q]) + wg[1][hh][e0 + 1] * bfhi(cg[q]) + wg[2][hh][e0 + 1] * bfhi(ng[q]) + wg[3][hh][e0 + 1];
;           resw[q] = pk2(siluf(ug0) * ua0, siluf(ug1) * ua1);
;         }
;         u32x4 w; w.x = resw[0]; w.y = resw[1]; w.z = resw[2]; w.w = resw[3];
;         __builtin_nontemporal_store(w, (GAS u32x4*)(ea.out + (size_t)(m0 + r) * 2816 + ja0 + j8));
	v_lshlrev_b32_e32 v66, 16, v162
	v_and_b32_e32 v67, 0xffff0000, v162
	v_lshlrev_b32_e32 v68, 16, v163
	v_and_b32_e32 v69, 0xffff0000, v163
	v_lshlrev_b32_e32 v70, 16, v164
	v_and_b32_e32 v71, 0xffff0000, v164
	v_lshlrev_b32_e32 v72, 16, v165
	v_and_b32_e32 v73, 0xffff0000, v165
	v_lshlrev_b32_e32 v74, 16, v166
	v_and_b32_e32 v75, 0xffff0000, v166
	v_lshlrev_b32_e32 v76, 16, v167
	v_and_b32_e32 v77, 0xffff0000, v167
	v_lshlrev_b32_e32 v78, 16, v168
	v_and_b32_e32 v79, 0xffff0000, v168
	v_lshlrev_b32_e32 v80, 16, v169
	v_and_b32_e32 v81, 0xffff0000, v169
	v_mul_f32_e32 v138, v10, v120
	v_mul_f32_e32 v139, v11, v121
	v_mul_f32_e32 v140, v12, v122
	v_mul_f32_e32 v141, v13, v123
	v_fma_f32 v104, v2, v104, v138
	v_fma_f32 v105, v3, v105, v139
	v_fma_f32 v106, v4, v106, v140
	v_fma_f32 v107, v5, v107, v141
	v_fma_f32 v104, v18, v66, v104
	v_fma_f32 v105, v19, v67, v105
	v_fma_f32 v106, v20, v68, v106
	v_fma_f32 v107, v21, v69, v107
	v_add_f32_e32 v104, v26, v104
	v_add_f32_e32 v105, v27, v105
	v_add_f32_e32 v106, v28, v106
	v_add_f32_e32 v107, v29, v107
	v_mul_f32_e32 v138, v14, v124
	v_mul_f32_e32 v139, v15, v125
	v_mul_f32_e32 v140, v16, v126
	v_mul_f32_e32 v141, v17, v127
	v_fma_f32 v108, v6, v108, v138
	v_fma_f32 v109, v7, v109, v139
	v_fma_f32 v110, v8, v110, v140
	v_fma_f32 v111, v9, v111, v141
	v_fma_f32 v108, v22, v70, v108
	v_fma_f32 v109, v23, v71, v109
	v_fma_f32 v110, v24, v72, v110
	v_fma_f32 v111, v25, v73, v111
	v_add_f32_e32 v108, v30, v108
	v_add_f32_e32 v109, v31, v109
	v_add_f32_e32 v110, v32, v110
	v_add_f32_e32 v111, v33, v111
	v_mul_f32_e32 v142, v42, v128
	v_mul_f32_e32 v143, v43, v129
	v_mul_f32_e32 v144, v44, v82
	v_mul_f32_e32 v145, v45, v83
	v_fma_f32 v112, v34, v112, v142
	v_fma_f32 v113, v35, v113, v143
	v_fma_f32 v114, v36, v114, v144
	v_fma_f32 v115, v37, v115, v145
	v_fma_f32 v112, v50, v74, v112
	v_fma_f32 v113, v51, v75, v113
	v_fma_f32 v114, v52, v76, v114
	v_fma_f32 v115, v53, v77, v115
	v_add_f32_e32 v112, v58, v112
	v_add_f32_e32 v113, v59, v113
	v_add_f32_e32 v114, v60, v114
	v_add_f32_e32 v115, v61, v115
	v_mul_f32_e32 v142, v46, v84
	v_mul_f32_e32 v143, v47, v85
	v_mul_f32_e32 v144, v48, v86
	v_mul_f32_e32 v145, v49, v87
	v_fma_f32 v116, v38, v116, v142
	v_fma_f32 v117, v39, v117, v143
	v_fma_f32 v118, v40, v118, v144
	v_fma_f32 v119, v41, v119, v145
	v_fma_f32 v116, v54, v78, v116
	v_fma_f32 v117, v55, v79, v117
	v_fma_f32 v118, v56, v80, v118
	v_fma_f32 v119, v57, v81, v119
	v_add_f32_e32 v116, v62, v116
	v_add_f32_e32 v117, v63, v117
	v_add_f32_e32 v118, v64, v118
	v_add_f32_e32 v119, v65, v119
	v_mul_f32_e32 v138, 0xbfb8aa3b, v112
	v_mul_f32_e32 v139, 0xbfb8aa3b, v113
	v_mul_f32_e32 v140, 0xbfb8aa3b, v114
	v_mul_f32_e32 v141, 0xbfb8aa3b, v115
	v_exp_f32_e32 v138, v138
	v_exp_f32_e32 v139, v139
	v_exp_f32_e32 v140, v140
	v_exp_f32_e32 v141, v141
	v_add_f32_e32 v138, 1.0, v138
	v_add_f32_e32 v139, 1.0, v139
	v_add_f32_e32 v140, 1.0, v140
	v_add_f32_e32 v141, 1.0, v141
	v_rcp_f32_e32 v138, v138
	v_rcp_f32_e32 v139, v139
	v_rcp_f32_e32 v140, v140
	v_rcp_f32_e32 v141, v141
	v_mul_f32_e32 v112, v112, v138
	v_mul_f32_e32 v113, v113, v139
	v_mul_f32_e32 v114, v114, v140
	v_mul_f32_e32 v115, v115, v141
	v_mul_f32_e32 v104, v104, v112
	v_mul_f32_e32 v105, v105, v113
	v_mul_f32_e32 v106, v106, v114
	v_mul_f32_e32 v107, v107, v115
	v_mul_f32_e32 v138, 0xbfb8aa3b, v116
	v_mul_f32_e32 v139, 0xbfb8aa3b, v117
	v_mul_f32_e32 v140, 0xbfb8aa3b, v118
	v_mul_f32_e32 v141, 0xbfb8aa3b, v119
	v_exp_f32_e32 v138, v138
	v_exp_f32_e32 v139, v139
	v_exp_f32_e32 v140, v140
	v_exp_f32_e32 v141, v141
	v_add_f32_e32 v138, 1.0, v138
	v_add_f32_e32 v139, 1.0, v139
	v_add_f32_e32 v140, 1.0, v140
	v_add_f32_e32 v141, 1.0, v141
	v_rcp_f32_e32 v138, v138
	v_rcp_f32_e32 v139, v139
	v_rcp_f32_e32 v140, v140
	v_rcp_f32_e32 v141, v141
	v_mul_f32_e32 v116, v116, v138
	v_mul_f32_e32 v117, v117, v139
	v_mul_f32_e32 v118, v118, v140
	v_mul_f32_e32 v119, v119, v141
	v_mul_f32_e32 v108, v108, v116
	v_mul_f32_e32 v109, v109, v117
	v_mul_f32_e32 v110, v110, v118
	v_mul_f32_e32 v111, v111, v119
	v_cvt_pk_bf16_f32 v100, v104, v105
	v_cvt_pk_bf16_f32 v101, v106, v107
	v_cvt_pk_bf16_f32 v102, v108, v109
	v_cvt_pk_bf16_f32 v103, v110, v111
	global_store_dwordx4 v[88:89], v[100:103], off nt
	v_lshl_add_u64 v[88:89], v[88:89], 0, s[10:11]
	s_waitcnt lgkmcnt(2)
; #define GAS __attribute__((address_space(1)))
; DI unsigned pk2(float a, float b) { f32x2 v = {a, b}; bf2_t r = __builtin_convertvector(v, bf2_t); return __builtin_bit_cast(unsigned, r); }
; DI float bflo(unsigned w) { return __uint_as_float(w << 16); }
; DI float bfhi(unsigned w) { return __uint_as_float(w & 0xffff0000u); }
; DI float siluf(float v) { return v * __builtin_amdgcn_rcpf(1.f + __builtin_amdgcn_exp2f(-1.4426950408889634f * v)); }
;     ...
;         const char* base = smem + r * 528 + (p * 128 + j8) * 2;
;         const u32x4 zz = {0u, 0u, 0u, 0u};
;         const u32x4 pa = top ? zz : *(const u32x4*)(base - 528), ca = *(const u32x4*)base, na = bot ? zz : *(const u32x4*)(base + 528);
;         const u32x4 pg = top ? zz : *(const u32x4*)(base - 528 + 128), cg = *(const u32x4*)(base + 128), ng = bot ? zz : *(const u32x4*)(base + 528 + 128);
;         unsigned resw[4];
; #pragma unroll
;         for (int q = 0; q < 4; ++q) {
;           const int hh = q >> 1, e0 = (q & 1) * 2;
;           const float ua0 = wa[0][hh][e0] * bflo(pa[q]) + wa[1][hh][e0] * bflo(ca[q]) + wa[2][hh][e0] * bflo(na[q]) + wa[3][hh][e0];
;           const float ua1 = wa[0][hh][e0 + 1] * bfhi(pa[q]) + wa[1][hh][e0 + 1] * bfhi(ca[q]) + wa[2][hh][e0 + 1] * bfhi(na[q]) + wa[3][hh][e0 + 1];
;           const float ug0 = wg[0][hh][e0] * bflo(pg[q]) + wg[1][hh][e0] * bflo(cg[q]) + wg[2][hh][e0] * bflo(ng[q]) + wg[3][hh][e0];
;           const float ug1 = wg[0][hh][e0 + 1] * bfhi(pg[q]) + wg[1][hh][e0 + 1] * bfhi(cg[q]) + wg[2][hh][e0 + 1] * bfhi(ng[q]) + wg[3][hh][e0 + 1];
;           resw[q] = pk2(siluf(ug0) * ua0, siluf(ug1) * ua1);
;         }
;         u32x4 w; w.x = resw[0]; w.y = resw[1]; w.z = resw[2]; w.w = resw[3];
;         __builtin_nontemporal_store(w, (GAS u32x4*)(ea.out + (size_t)(m0 + r) * 2816 + ja0 + j8));
	v_lshlrev_b32_e32 v104, 16, v170
	v_and_b32_e32 v105, 0xffff0000, v170
	v_lshlrev_b32_e32 v106, 16, v171
	v_and_b32_e32 v107, 0xffff0000, v171
	v_lshlrev_b32_e32 v108, 16, v172
	v_and_b32_e32 v109, 0xffff0000, v172
	v_lshlrev_b32_e32 v110, 16, v173
	v_and_b32_e32 v111, 0xffff0000, v173
	v_lshlrev_b32_e32 v112, 16, v174
	v_and_b32_e32 v113, 0xffff0000, v174
	v_lshlrev_b32_e32 v114, 16, v175
	v_and_b32_e32 v115, 0xffff0000, v175
	v_lshlrev_b32_e32 v116, 16, v176
	v_and_b32_e32 v117, 0xffff0000, v176
	v_lshlrev_b32_e32 v118, 16, v177
	v_and_b32_e32 v119, 0xffff0000, v177
	ds_read_b128 v[146:149], v94 offset:2640
	ds_read_b128 v[150:153], v94 offset:2768
	ds_read_b128 v[154:157], v94 offset:3168
	ds_read_b128 v[158:161], v94 offset:3296
	ds_read_b128 v[162:165], v94 offset:3696
	ds_read_b128 v[166:169], v94 offset:3824
	ds_read_b128 v[170:173], v94 offset:4224
	ds_read_b128 v[174:177], v94 offset:4352
	v_mul_f32_e32 v138, v10, v66
	v_mul_f32_e32 v139, v11, v67
	v_mul_f32_e32 v140, v12, v68
	v_mul_f32_e32 v141, v13, v69
	v_fma_f32 v120, v2, v120, v138
	v_fma_f32 v121, v3, v121, v139
	v_fma_f32 v122, v4, v122, v140
	v_fma_f32 v123, v5, v123, v141
	v_fma_f32 v120, v18, v104, v120
	v_fma_f32 v121, v19, v105, v121
	v_fma_f32 v122, v20, v106, v122
	v_fma_f32 v123, v21, v107, v123
	v_add_f32_e32 v120, v26, v120
	v_add_f32_e32 v121, v27, v121
	v_add_f32_e32 v122, v28, v122
	v_add_f32_e32 v123, v29, v123
	v_mul_f32_e32 v138, v14, v70
	v_mul_f32_e32 v139, v15, v71
	v_mul_f32_e32 v140, v16, v72
	v_mul_f32_e32 v141, v17, v73
	v_fma_f32 v124, v6, v124, v138
	v_fma_f32 v125, v7, v125, v139
	v_fma_f32 v126, v8, v126, v140
	v_fma_f32 v127, v9, v127, v141
	v_fma_f32 v124, v22, v108, v124
	v_fma_f32 v125, v23, v109, v125
	v_fma_f32 v126, v24, v110, v126
	v_fma_f32 v127, v25, v111, v127
	v_add_f32_e32 v124, v30, v124
	v_add_f32_e32 v125, v31, v125
	v_add_f32_e32 v126, v32, v126
	v_add_f32_e32 v127, v33, v127
	v_mul_f32_e32 v142, v42, v74
	v_mul_f32_e32 v143, v43, v75
	v_mul_f32_e32 v144, v44, v76
	v_mul_f32_e32 v145, v45, v77
	v_fma_f32 v128, v34, v128, v142
	v_fma_f32 v129, v35, v129, v143
	v_fma_f32 v82, v36, v82, v144
	v_fma_f32 v83, v37, v83, v145
	v_fma_f32 v128, v50, v112, v128
	v_fma_f32 v129, v51, v113, v129
	v_fma_f32 v82, v52, v114, v82
	v_fma_f32 v83, v53, v115, v83
	v_add_f32_e32 v128, v58, v128
	v_add_f32_e32 v129, v59, v129
	v_add_f32_e32 v82, v60, v82
	v_add_f32_e32 v83, v61, v83
	v_mul_f32_e32 v142, v46, v78
	v_mul_f32_e32 v143, v47, v79
	v_mul_f32_e32 v144, v48, v80
	v_mul_f32_e32 v145, v49, v81
	v_fma_f32 v84, v38, v84, v142
	v_fma_f32 v85, v39, v85, v143
	v_fma_f32 v86, v40, v86, v144
	v_fma_f32 v87, v41, v87, v145
	v_fma_f32 v84, v54, v116, v84
	v_fma_f32 v85, v55, v117, v85
	v_fma_f32 v86, v56, v118, v86
	v_fma_f32 v87, v57, v119, v87
	v_add_f32_e32 v84, v62, v84
	v_add_f32_e32 v85, v63, v85
	v_add_f32_e32 v86, v64, v86
	v_add_f32_e32 v87, v65, v87
	v_mul_f32_e32 v138, 0xbfb8aa3b, v128
	v_mul_f32_e32 v139, 0xbfb8aa3b, v129
	v_mul_f32_e32 v140, 0xbfb8aa3b, v82
	v_mul_f32_e32 v141, 0xbfb8aa3b, v83
	v_exp_f32_e32 v138, v138
	v_exp_f32_e32 v139, v139
	v_exp_f32_e32 v140, v140
	v_exp_f32_e32 v141, v141
	v_add_f32_e32 v138, 1.0, v138
	v_add_f32_e32 v139, 1.0, v139
	v_add_f32_e32 v140, 1.0, v140
	v_add_f32_e32 v141, 1.0, v141
	v_rcp_f32_e32 v138, v138
	v_rcp_f32_e32 v139, v139
	v_rcp_f32_e32 v140, v140
	v_rcp_f32_e32 v141, v141
	v_mul_f32_e32 v128, v128, v138
	v_mul_f32_e32 v129, v129, v139
	v_mul_f32_e32 v82, v82, v140
	v_mul_f32_e32 v83, v83, v141
	v_mul_f32_e32 v120, v120, v128
	v_mul_f32_e32 v121, v121, v129
	v_mul_f32_e32 v122, v122, v82
	v_mul_f32_e32 v123, v123, v83
	v_mul_f32_e32 v138, 0xbfb8aa3b, v84
	v_mul_f32_e32 v139, 0xbfb8aa3b, v85
	v_mul_f32_e32 v140, 0xbfb8aa3b, v86
	v_mul_f32_e32 v141, 0xbfb8aa3b, v87
	v_exp_f32_e32 v138, v138
	v_exp_f32_e32 v139, v139
	v_exp_f32_e32 v140, v140
	v_exp_f32_e32 v141, v141
	v_add_f32_e32 v138, 1.0, v138
	v_add_f32_e32 v139, 1.0, v139
	v_add_f32_e32 v140, 1.0, v140
	v_add_f32_e32 v141, 1.0, v141
	v_rcp_f32_e32 v138, v138
	v_rcp_f32_e32 v139, v139
	v_rcp_f32_e32 v140, v140
	v_rcp_f32_e32 v141, v141
	v_mul_f32_e32 v84, v84, v138
	v_mul_f32_e32 v85, v85, v139
	v_mul_f32_e32 v86, v86, v140
	v_mul_f32_e32 v87, v87, v141
	v_mul_f32_e32 v124, v124, v84
	v_mul_f32_e32 v125, v125, v85
	v_mul_f32_e32 v126, v126, v86
	v_mul_f32_e32 v127, v127, v87
	v_cvt_pk_bf16_f32 v100, v120, v121
	v_cvt_pk_bf16_f32 v101, v122, v123
	v_cvt_pk_bf16_f32 v102, v124, v125
	v_cvt_pk_bf16_f32 v103, v126, v127
	global_store_dwordx4 v[88:89], v[100:103], off nt
	v_lshl_add_u64 v[88:89], v[88:89], 0, s[10:11]
	s_waitcnt lgkmcnt(8)
; #define GAS __attribute__((address_space(1)))
; DI unsigned pk2(float a, float b) { f32x2 v = {a, b}; bf2_t r = __builtin_convertvector(v, bf2_t); return __builtin_bit_cast(unsigned, r); }
; DI float bflo(unsigned w) { return __uint_as_float(w << 16); }
; DI float bfhi(unsigned w) { return __uint_as_float(w & 0xffff0000u); }
; DI float siluf(float v) { return v * __builtin_amdgcn_rcpf(1.f + __builtin_amdgcn_exp2f(-1.4426950408889634f * v)); }
;     ...
;         const char* base = smem + r * 528 + (p * 128 + j8) * 2;
;         const u32x4 zz = {0u, 0u, 0u, 0u};
;         const u32x4 pa = top ? zz : *(const u32x4*)(base - 528), ca = *(const u32x4*)base, na = bot ? zz : *(const u32x4*)(base + 528);
;         const u32x4 pg = top ? zz : *(const u32x4*)(base - 528 + 128), cg = *(const u32x4*)(base + 128), ng = bot ? zz : *(const u32x4*)(base + 528 + 128);
;         unsigned resw[4];
; #pragma unroll
;         for (int q = 0; q < 4; ++q) {
;           const int hh = q >> 1, e0 = (q & 1) * 2;
;           const float ua0 = wa[0][hh][e0] * bflo(pa[q]) + wa[1][hh][e0] * bflo(ca[q]) + wa[2][hh][e0] * bflo(na[q]) + wa[3][hh][e0];
;           const float ua1 = wa[0][hh][e0 + 1] * bfhi(pa[q]) + wa[1][hh][e0 + 1] * bfhi(ca[q]) + wa[2][hh][e0 + 1] * bfhi(na[q]) + wa[3][hh][e0 + 1];
;           const float ug0 = wg[0][hh][e0] * bflo(pg[q]) + wg[1][hh][e0] * bflo(cg[q]) + wg[2][hh][e0] * bflo(ng[q]) + wg[3][hh][e0];
;           const float ug1 = wg[0][hh][e0 + 1] * bfhi(pg[q]) + wg[1][hh][e0 + 1] * bfhi(cg[q]) + wg[2][hh][e0 + 1] * bfhi(ng[q]) + wg[3][hh][e0 + 1];
;           resw[q] = pk2(siluf(ug0) * ua0, siluf(ug1) * ua1);
;         }
;         u32x4 w; w.x = resw[0]; w.y = resw[1]; w.z = resw[2]; w.w = resw[3];
;         __builtin_nontemporal_store(w, (GAS u32x4*)(ea.out + (size_t)(m0 + r) * 2816 + ja0 + j8));
	v_lshlrev_b32_e32 v120, 16, v178
	v_and_b32_e32 v121, 0xffff0000, v178
	v_lshlrev_b32_e32 v122, 16, v179
	v_and_b32_e32 v123, 0xffff0000, v179
	v_lshlrev_b32_e32 v124, 16, v180
	v_and_b32_e32 v125, 0xffff0000, v180
	v_lshlrev_b32_e32 v126, 16, v181
	v_and_b32_e32 v127, 0xffff0000, v181
	v_lshlrev_b32_e32 v128, 16, v182
	v_and_b32_e32 v129, 0xffff0000, v182
	v_lshlrev_b32_e32 v82, 16, v183
	v_and_b32_e32 v83, 0xffff0000, v183
	v_lshlrev_b32_e32 v84, 16, v184
	v_and_b32_e32 v85, 0xffff0000, v184
	v_lshlrev_b32_e32 v86, 16, v185
	v_and_b32_e32 v87, 0xffff0000, v185
	v_mul_f32_e32 v138, v10, v104
	v_mul_f32_e32 v139, v11, v105
	v_mul_f32_e32 v140, v12, v106
	v_mul_f32_e32 v141, v13, v107
	v_fma_f32 v66, v2, v66, v138
	v_fma_f32 v67, v3, v67, v139
	v_fma_f32 v68, v4, v68, v140
	v_fma_f32 v69, v5, v69, v141
	v_fma_f32 v66, v18, v120, v66
	v_fma_f32 v67, v19, v121, v67
	v_fma_f32 v68, v20, v122, v68
	v_fma_f32 v69, v21, v123, v69
	v_add_f32_e32 v66, v26, v66
	v_add_f32_e32 v67, v27, v67
	v_add_f32_e32 v68, v28, v68
	v_add_f32_e32 v69, v29, v69
	v_mul_f32_e32 v138, v14, v108
	v_mul_f32_e32 v139, v15, v109
	v_mul_f32_e32 v140, v16, v110
	v_mul_f32_e32 v141, v17, v111
	v_fma_f32 v70, v6, v70, v138
	v_fma_f32 v71, v7, v71, v139
	v_fma_f32 v72, v8, v72, v140
	v_fma_f32 v73, v9, v73, v141
	v_fma_f32 v70, v22, v124, v70
	v_fma_f32 v71, v23, v125, v71
	v_fma_f32 v72, v24, v126, v72
	v_fma_f32 v73, v25, v127, v73
	v_add_f32_e32 v70, v30, v70
	v_add_f32_e32 v71, v31, v71
	v_add_f32_e32 v72, v32, v72
	v_add_f32_e32 v73, v33, v73
	v_mul_f32_e32 v142, v42, v112
	v_mul_f32_e32 v143, v43, v113
	v_mul_f32_e32 v144, v44, v114
	v_mul_f32_e32 v145, v45, v115
	v_fma_f32 v74, v34, v74, v142
	v_fma_f32 v75, v35, v75, v143
	v_fma_f32 v76, v36, v76, v144
	v_fma_f32 v77, v37, v77, v145
	v_fma_f32 v74, v50, v128, v74
	v_fma_f32 v75, v51, v129, v75
	v_fma_f32 v76, v52, v82, v76
	v_fma_f32 v77, v53, v83, v77
	v_add_f32_e32 v74, v58, v74
	v_add_f32_e32 v75, v59, v75
	v_add_f32_e32 v76, v60, v76
	v_add_f32_e32 v77, v61, v77
	v_mul_f32_e32 v142, v46, v116
	v_mul_f32_e32 v143, v47, v117
	v_mul_f32_e32 v144, v48, v118
	v_mul_f32_e32 v145, v49, v119
	v_fma_f32 v78, v38, v78, v142
	v_fma_f32 v79, v39, v79, v143
	v_fma_f32 v80, v40, v80, v144
	v_fma_f32 v81, v41, v81, v145
	v_fma_f32 v78, v54, v84, v78
	v_fma_f32 v79, v55, v85, v79
	v_fma_f32 v80, v56, v86, v80
	v_fma_f32 v81, v57, v87, v81
	v_add_f32_e32 v78, v62, v78
	v_add_f32_e32 v79, v63, v79
	v_add_f32_e32 v80, v64, v80
	v_add_f32_e32 v81, v65, v81
	v_mul_f32_e32 v138, 0xbfb8aa3b, v74
	v_mul_f32_e32 v139, 0xbfb8aa3b, v75
	v_mul_f32_e32 v140, 0xbfb8aa3b, v76
	v_mul_f32_e32 v141, 0xbfb8aa3b, v77
	v_exp_f32_e32 v138, v138
	v_exp_f32_e32 v139, v139
	v_exp_f32_e32 v140, v140
	v_exp_f32_e32 v141, v141
	v_add_f32_e32 v138, 1.0, v138
	v_add_f32_e32 v139, 1.0, v139
	v_add_f32_e32 v140, 1.0, v140
	v_add_f32_e32 v141, 1.0, v141
	v_rcp_f32_e32 v138, v138
	v_rcp_f32_e32 v139, v139
	v_rcp_f32_e32 v140, v140
	v_rcp_f32_e32 v141, v141
	v_mul_f32_e32 v74, v74, v138
	v_mul_f32_e32 v75, v75, v139
	v_mul_f32_e32 v76, v76, v140
	v_mul_f32_e32 v77, v77, v141
	v_mul_f32_e32 v66, v66, v74
	v_mul_f32_e32 v67, v67, v75
	v_mul_f32_e32 v68, v68, v76
	v_mul_f32_e32 v69, v69, v77
	v_mul_f32_e32 v138, 0xbfb8aa3b, v78
	v_mul_f32_e32 v139, 0xbfb8aa3b, v79
	v_mul_f32_e32 v140, 0xbfb8aa3b, v80
	v_mul_f32_e32 v141, 0xbfb8aa3b, v81
	v_exp_f32_e32 v138, v138
	v_exp_f32_e32 v139, v139
	v_exp_f32_e32 v140, v140
	v_exp_f32_e32 v141, v141
	v_add_f32_e32 v138, 1.0, v138
	v_add_f32_e32 v139, 1.0, v139
	v_add_f32_e32 v140, 1.0, v140
	v_add_f32_e32 v141, 1.0, v141
	v_rcp_f32_e32 v138, v138
	v_rcp_f32_e32 v139, v139
	v_rcp_f32_e32 v140, v140
	v_rcp_f32_e32 v141, v141
	v_mul_f32_e32 v78, v78, v138
	v_mul_f32_e32 v79, v79, v139
	v_mul_f32_e32 v80, v80, v140
	v_mul_f32_e32 v81, v81, v141
	v_mul_f32_e32 v70, v70, v78
	v_mul_f32_e32 v71, v71, v79
	v_mul_f32_e32 v72, v72, v80
	v_mul_f32_e32 v73, v73, v81
	v_cvt_pk_bf16_f32 v100, v66, v67
	v_cvt_pk_bf16_f32 v101, v68, v69
	v_cvt_pk_bf16_f32 v102, v70, v71
	v_cvt_pk_bf16_f32 v103, v72, v73
	global_store_dwordx4 v[88:89], v[100:103], off nt
	v_lshl_add_u64 v[88:89], v[88:89], 0, s[10:11]
	s_waitcnt lgkmcnt(6)
	v_lshlrev_b32_e32 v66, 16, v146
	v_and_b32_e32 v67, 0xffff0000, v146
	v_lshlrev_b32_e32 v68, 16, v147
	v_and_b32_e32 v69, 0xffff0000, v147
	v_lshlrev_b32_e32 v70, 16, v148
	v_and_b32_e32 v71, 0xffff0000, v148
	v_lshlrev_b32_e32 v72, 16, v149
	v_and_b32_e32 v73, 0xffff0000, v149
	v_lshlrev_b32_e32 v74, 16, v150
	v_and_b32_e32 v75, 0xffff0000, v150
	v_lshlrev_b32_e32 v76, 16, v151
	v_and_b32_e32 v77, 0xffff0000, v151
	v_lshlrev_b32_e32 v78, 16, v152
	v_and_b32_e32 v79, 0xffff0000, v152
	v_lshlrev_b32_e32 v80, 16, v153
	v_and_b32_e32 v81, 0xffff0000, v153
	v_mul_f32_e32 v138, v10, v120
	v_mul_f32_e32 v139, v11, v121
	v_mul_f32_e32 v140, v12, v122
	v_mul_f32_e32 v141, v13, v123
	v_fma_f32 v104, v2, v104, v138
	v_fma_f32 v105, v3, v105, v139
	v_fma_f32 v106, v4, v106, v140
	v_fma_f32 v107, v5, v107, v141
	v_fma_f32 v104, v18, v66, v104
	v_fma_f32 v105, v19, v67, v105
	v_fma_f32 v106, v20, v68, v106
	v_fma_f32 v107, v21, v69, v107
	v_add_f32_e32 v104, v26, v104
	v_add_f32_e32 v105, v27, v105
	v_add_f32_e32 v106, v28, v106
	v_add_f32_e32 v107, v29, v107
	v_mul_f32_e32 v138, v14, v124
	v_mul_f32_e32 v139, v15, v125
	v_mul_f32_e32 v140, v16, v126
	v_mul_f32_e32 v141, v17, v127
	v_fma_f32 v108, v6, v108, v138
	v_fma_f32 v109, v7, v109, v139
	v_fma_f32 v110, v8, v110, v140
	v_fma_f32 v111, v9, v111, v141
	v_fma_f32 v108, v22, v70, v108
	v_fma_f32 v109, v23, v71, v109
	v_fma_f32 v110, v24, v72, v110
	v_fma_f32 v111, v25, v73, v111
; #define GAS __attribute__((address_space(1)))
; DI unsigned pk2(float a, float b) { f32x2 v = {a, b}; bf2_t r = __builtin_convertvector(v, bf2_t); return __builtin_bit_cast(unsigned, r); }
; DI float bflo(unsigned w) { return __uint_as_float(w << 16); }
; DI float bfhi(unsigned w) { return __uint_as_float(w & 0xffff0000u); }
; DI float siluf(float v) { return v * __builtin_amdgcn_rcpf(1.f + __builtin_amdgcn_exp2f(-1.4426950408889634f * v)); }
;     ...
;         for (int q = 0; q < 4; ++q) {
;           const int hh = q >> 1, e0 = (q & 1) * 2;
;           const float ua0 = wa[0][hh][e0] * bflo(pa[q]) + wa[1][hh][e0] * bflo(ca[q]) + wa[2][hh][e0] * bflo(na[q]) + wa[3][hh][e0];
;           const float ua1 = wa[0][hh][e0 + 1] * bfhi(pa[q]) + wa[1][hh][e0 + 1] * bfhi(ca[q]) + wa[2][hh][e0 + 1] * bfhi(na[q]) + wa[3][hh][e0 + 1];
;           const float ug0 = wg[0][hh][e0] * bflo(pg[q]) + wg[1][hh][e0] * bflo(cg[q]) + wg[2][hh][e0] * bflo(ng[q]) + wg[3][hh][e0];
;           const float ug1 = wg[0][hh][e0 + 1] * bfhi(pg[q]) + wg[1][hh][e0 + 1] * bfhi(cg[q]) + wg[2][hh][e0 + 1] * bfhi(ng[q]) + wg[3][hh][e0 + 1];
;           resw[q] = pk2(siluf(ug0) * ua0, siluf(ug1) * ua1);
;         }
;         u32x4 w; w.x = resw[0]; w.y = resw[1]; w.z = resw[2]; w.w = resw[3];
;         __builtin_nontemporal_store(w, (GAS u32x4*)(ea.out + (size_t)(m0 + r) * 2816 + ja0 + j8));
	v_add_f32_e32 v108, v30, v108
	v_add_f32_e32 v109, v31, v109
	v_add_f32_e32 v110, v32, v110
	v_add_f32_e32 v111, v33, v111
	v_mul_f32_e32 v142, v42, v128
	v_mul_f32_e32 v143, v43, v129
	v_mul_f32_e32 v144, v44, v82
	v_mul_f32_e32 v145, v45, v83
	v_fma_f32 v112, v34, v112, v142
	v_fma_f32 v113, v35, v113, v143
	v_fma_f32 v114, v36, v114, v144
	v_fma_f32 v115, v37, v115, v145
	v_fma_f32 v112, v50, v74, v112
	v_fma_f32 v113, v51, v75, v113
	v_fma_f32 v114, v52, v76, v114
	v_fma_f32 v115, v53, v77, v115
	v_add_f32_e32 v112, v58, v112
	v_add_f32_e32 v113, v59, v113
	v_add_f32_e32 v114, v60, v114
	v_add_f32_e32 v115, v61, v115
	v_mul_f32_e32 v142, v46, v84
	v_mul_f32_e32 v143, v47, v85
	v_mul_f32_e32 v144, v48, v86
	v_mul_f32_e32 v145, v49, v87
	v_fma_f32 v116, v38, v116, v142
	v_fma_f32 v117, v39, v117, v143
	v_fma_f32 v118, v40, v118, v144
	v_fma_f32 v119, v41, v119, v145
	v_fma_f32 v116, v54, v78, v116
	v_fma_f32 v117, v55, v79, v117
	v_fma_f32 v118, v56, v80, v118
	v_fma_f32 v119, v57, v81, v119
	v_add_f32_e32 v116, v62, v116
	v_add_f32_e32 v117, v63, v117
	v_add_f32_e32 v118, v64, v118
	v_add_f32_e32 v119, v65, v119
	v_mul_f32_e32 v138, 0xbfb8aa3b, v112
	v_mul_f32_e32 v139, 0xbfb8aa3b, v113
	v_mul_f32_e32 v140, 0xbfb8aa3b, v114
	v_mul_f32_e32 v141, 0xbfb8aa3b, v115
	v_exp_f32_e32 v138, v138
	v_exp_f32_e32 v139, v139
	v_exp_f32_e32 v140, v140
	v_exp_f32_e32 v141, v141
	v_add_f32_e32 v138, 1.0, v138
	v_add_f32_e32 v139, 1.0, v139
	v_add_f32_e32 v140, 1.0, v140
	v_add_f32_e32 v141, 1.0, v141
	v_rcp_f32_e32 v138, v138
	v_rcp_f32_e32 v139, v139
	v_rcp_f32_e32 v140, v140
	v_rcp_f32_e32 v141, v141
	v_mul_f32_e32 v112, v112, v138
	v_mul_f32_e32 v113, v113, v139
	v_mul_f32_e32 v114, v114, v140
	v_mul_f32_e32 v115, v115, v141
	v_mul_f32_e32 v104, v104, v112
	v_mul_f32_e32 v105, v105, v113
	v_mul_f32_e32 v106, v106, v114
	v_mul_f32_e32 v107, v107, v115
	v_mul_f32_e32 v138, 0xbfb8aa3b, v116
	v_mul_f32_e32 v139, 0xbfb8aa3b, v117
	v_mul_f32_e32 v140, 0xbfb8aa3b, v118
	v_mul_f32_e32 v141, 0xbfb8aa3b, v119
	v_exp_f32_e32 v138, v138
	v_exp_f32_e32 v139, v139
	v_exp_f32_e32 v140, v140
	v_exp_f32_e32 v141, v141
	v_add_f32_e32 v138, 1.0, v138
	v_add_f32_e32 v139, 1.0, v139
	v_add_f32_e32 v140, 1.0, v140
	v_add_f32_e32 v141, 1.0, v141
	v_rcp_f32_e32 v138, v138
	v_rcp_f32_e32 v139, v139
	v_rcp_f32_e32 v140, v140
	v_rcp_f32_e32 v141, v141
	v_mul_f32_e32 v116, v116, v138
	v_mul_f32_e32 v117, v117, v139
	v_mul_f32_e32 v118, v118, v140
	v_mul_f32_e32 v119, v119, v141
	v_mul_f32_e32 v108, v108, v116
	v_mul_f32_e32 v109, v109, v117
	v_mul_f32_e32 v110, v110, v118
	v_mul_f32_e32 v111, v111, v119
	v_cvt_pk_bf16_f32 v100, v104, v105
	v_cvt_pk_bf16_f32 v101, v106, v107
	v_cvt_pk_bf16_f32 v102, v108, v109
	v_cvt_pk_bf16_f32 v103, v110, v111
	global_store_dwordx4 v[88:89], v[100:103], off nt
	v_lshl_add_u64 v[88:89], v[88:89], 0, s[10:11]
	s_waitcnt lgkmcnt(4)
	v_lshlrev_b32_e32 v104, 16, v154
	v_and_b32_e32 v105, 0xffff0000, v154
	v_lshlrev_b32_e32 v106, 16, v155
	v_and_b32_e32 v107, 0xffff0000, v155
	v_lshlrev_b32_e32 v108, 16, v156
	v_and_b32_e32 v109, 0xffff0000, v156
	v_lshlrev_b32_e32 v110, 16, v157
	v_and_b32_e32 v111, 0xffff0000, v157
	v_lshlrev_b32_e32 v112, 16, v158
	v_and_b32_e32 v113, 0xffff0000, v158
	v_lshlrev_b32_e32 v114, 16, v159
	v_and_b32_e32 v115, 0xffff0000, v159
	v_lshlrev_b32_e32 v116, 16, v160
	v_and_b32_e32 v117, 0xffff0000, v160
	v_lshlrev_b32_e32 v118, 16, v161
	v_and_b32_e32 v119, 0xffff0000, v161
	v_mul_f32_e32 v138, v10, v66
	v_mul_f32_e32 v139, v11, v67
	v_mul_f32_e32 v140, v12, v68
	v_mul_f32_e32 v141, v13, v69
	v_fma_f32 v120, v2, v120, v138
	v_fma_f32 v121, v3, v121, v139
	v_fma_f32 v122, v4, v122, v140
	v_fma_f32 v123, v5, v123, v141
	v_fma_f32 v120, v18, v104, v120
	v_fma_f32 v121, v19, v105, v121
	v_fma_f32 v122, v20, v106, v122
	v_fma_f32 v123, v21, v107, v123
	v_add_f32_e32 v120, v26, v120
	v_add_f32_e32 v121, v27, v121
	v_add_f32_e32 v122, v28, v122
	v_add_f32_e32 v123, v29, v123
	v_mul_f32_e32 v138, v14, v70
	v_mul_f32_e32 v139, v15, v71
	v_mul_f32_e32 v140, v16, v72
	v_mul_f32_e32 v141, v17, v73
	v_fma_f32 v124, v6, v124, v138
	v_fma_f32 v125, v7, v125, v139
	v_fma_f32 v126, v8, v126, v140
	v_fma_f32 v127, v9, v127, v141
	v_fma_f32 v124, v22, v108, v124
	v_fma_f32 v125, v23, v109, v125
	v_fma_f32 v126, v24, v110, v126
	v_fma_f32 v127, v25, v111, v127
	v_add_f32_e32 v124, v30, v124
	v_add_f32_e32 v125, v31, v125
	v_add_f32_e32 v126, v32, v126
	v_add_f32_e32 v127, v33, v127
	v_mul_f32_e32 v142, v42, v74
	v_mul_f32_e32 v143, v43, v75
	v_mul_f32_e32 v144, v44, v76
	v_mul_f32_e32 v145, v45, v77
	v_fma_f32 v128, v34, v128, v142
	v_fma_f32 v129, v35, v129, v143
	v_fma_f32 v82, v36, v82, v144
	v_fma_f32 v83, v37, v83, v145
	v_fma_f32 v128, v50, v112, v128
	v_fma_f32 v129, v51, v113, v129
	v_fma_f32 v82, v52, v114, v82
	v_fma_f32 v83, v53, v115, v83
	v_add_f32_e32 v128, v58, v128
	v_add_f32_e32 v129, v59, v129
	v_add_f32_e32 v82, v60, v82
	v_add_f32_e32 v83, v61, v83
	v_mul_f32_e32 v142, v46, v78
	v_mul_f32_e32 v143, v47, v79
	v_mul_f32_e32 v144, v48, v80
	v_mul_f32_e32 v145, v49, v81
	v_fma_f32 v84, v38, v84, v142
	v_fma_f32 v85, v39, v85, v143
	v_fma_f32 v86, v40, v86, v144
	v_fma_f32 v87, v41, v87, v145
	v_fma_f32 v84, v54, v116, v84
	v_fma_f32 v85, v55, v117, v85
	v_fma_f32 v86, v56, v118, v86
	v_fma_f32 v87, v57, v119, v87
	v_add_f32_e32 v84, v62, v84
	v_add_f32_e32 v85, v63, v85
	v_add_f32_e32 v86, v64, v86
	v_add_f32_e32 v87, v65, v87
	v_mul_f32_e32 v138, 0xbfb8aa3b, v128
	v_mul_f32_e32 v139, 0xbfb8aa3b, v129
	v_mul_f32_e32 v140, 0xbfb8aa3b, v82
	v_mul_f32_e32 v141, 0xbfb8aa3b, v83
	v_exp_f32_e32 v138, v138
	v_exp_f32_e32 v139, v139
; #define GAS __attribute__((address_space(1)))
; DI unsigned pk2(float a, float b) { f32x2 v = {a, b}; bf2_t r = __builtin_convertvector(v, bf2_t); return __builtin_bit_cast(unsigned, r); }
; DI float bflo(unsigned w) { return __uint_as_float(w << 16); }
; DI float bfhi(unsigned w) { return __uint_as_float(w & 0xffff0000u); }
; DI float siluf(float v) { return v * __builtin_amdgcn_rcpf(1.f + __builtin_amdgcn_exp2f(-1.4426950408889634f * v)); }
;     ...
;         const char* base = smem + r * 528 + (p * 128 + j8) * 2;
;         const u32x4 zz = {0u, 0u, 0u, 0u};
;         const u32x4 pa = top ? zz : *(const u32x4*)(base - 528), ca = *(const u32x4*)base, na = bot ? zz : *(const u32x4*)(base + 528);
;         const u32x4 pg = top ? zz : *(const u32x4*)(base - 528 + 128), cg = *(const u32x4*)(base + 128), ng = bot ? zz : *(const u32x4*)(base + 528 + 128);
;         unsigned resw[4];
; #pragma unroll
;         for (int q = 0; q < 4; ++q) {
;           const int hh = q >> 1, e0 = (q & 1) * 2;
;           const float ua0 = wa[0][hh][e0] * bflo(pa[q]) + wa[1][hh][e0] * bflo(ca[q]) + wa[2][hh][e0] * bflo(na[q]) + wa[3][hh][e0];
;           const float ua1 = wa[0][hh][e0 + 1] * bfhi(pa[q]) + wa[1][hh][e0 + 1] * bfhi(ca[q]) + wa[2][hh][e0 + 1] * bfhi(na[q]) + wa[3][hh][e0 + 1];
;           const float ug0 = wg[0][hh][e0] * bflo(pg[q]) + wg[1][hh][e0] * bflo(cg[q]) + wg[2][hh][e0] * bflo(ng[q]) + wg[3][hh][e0];
;           const float ug1 = wg[0][hh][e0 + 1] * bfhi(pg[q]) + wg[1][hh][e0 + 1] * bfhi(cg[q]) + wg[2][hh][e0 + 1] * bfhi(ng[q]) + wg[3][hh][e0 + 1];
;           resw[q] = pk2(siluf(ug0) * ua0, siluf(ug1) * ua1);
;         }
;         u32x4 w; w.x = resw[0]; w.y = resw[1]; w.z = resw[2]; w.w = resw[3];
;         __builtin_nontemporal_store(w, (GAS u32x4*)(ea.out + (size_t)(m0 + r) * 2816 + ja0 + j8));
	v_exp_f32_e32 v140, v140
	v_exp_f32_e32 v141, v141
	v_add_f32_e32 v138, 1.0, v138
	v_add_f32_e32 v139, 1.0, v139
	v_add_f32_e32 v140, 1.0, v140
	v_add_f32_e32 v141, 1.0, v141
	v_rcp_f32_e32 v138, v138
	v_rcp_f32_e32 v139, v139
	v_rcp_f32_e32 v140, v140
	v_rcp_f32_e32 v141, v141
	v_mul_f32_e32 v128, v128, v138
	v_mul_f32_e32 v129, v129, v139
	v_mul_f32_e32 v82, v82, v140
	v_mul_f32_e32 v83, v83, v141
	v_mul_f32_e32 v120, v120, v128
	v_mul_f32_e32 v121, v121, v129
	v_mul_f32_e32 v122, v122, v82
	v_mul_f32_e32 v123, v123, v83
	v_mul_f32_e32 v138, 0xbfb8aa3b, v84
	v_mul_f32_e32 v139, 0xbfb8aa3b, v85
	v_mul_f32_e32 v140, 0xbfb8aa3b, v86
	v_mul_f32_e32 v141, 0xbfb8aa3b, v87
	v_exp_f32_e32 v138, v138
	v_exp_f32_e32 v139, v139
	v_exp_f32_e32 v140, v140
	v_exp_f32_e32 v141, v141
	v_add_f32_e32 v138, 1.0, v138
	v_add_f32_e32 v139, 1.0, v139
	v_add_f32_e32 v140, 1.0, v140
	v_add_f32_e32 v141, 1.0, v141
	v_rcp_f32_e32 v138, v138
	v_rcp_f32_e32 v139, v139
	v_rcp_f32_e32 v140, v140
	v_rcp_f32_e32 v141, v141
	v_mul_f32_e32 v84, v84, v138
	v_mul_f32_e32 v85, v85, v139
	v_mul_f32_e32 v86, v86, v140
	v_mul_f32_e32 v87, v87, v141
	v_mul_f32_e32 v124, v124, v84
	v_mul_f32_e32 v125, v125, v85
	v_mul_f32_e32 v126, v126, v86
	v_mul_f32_e32 v127, v127, v87
	v_cvt_pk_bf16_f32 v100, v120, v121
	v_cvt_pk_bf16_f32 v101, v122, v123
	v_cvt_pk_bf16_f32 v102, v124, v125
	v_cvt_pk_bf16_f32 v103, v126, v127
	global_store_dwordx4 v[88:89], v[100:103], off nt
	v_lshl_add_u64 v[88:89], v[88:89], 0, s[10:11]
	s_waitcnt lgkmcnt(2)
	v_lshlrev_b32_e32 v120, 16, v162
	v_and_b32_e32 v121, 0xffff0000, v162
	v_lshlrev_b32_e32 v122, 16, v163
	v_and_b32_e32 v123, 0xffff0000, v163
	v_lshlrev_b32_e32 v124, 16, v164
	v_and_b32_e32 v125, 0xffff0000, v164
	v_lshlrev_b32_e32 v126, 16, v165
	v_and_b32_e32 v127, 0xffff0000, v165
	v_lshlrev_b32_e32 v128, 16, v166
	v_and_b32_e32 v129, 0xffff0000, v166
	v_lshlrev_b32_e32 v82, 16, v167
	v_and_b32_e32 v83, 0xffff0000, v167
	v_lshlrev_b32_e32 v84, 16, v168
	v_and_b32_e32 v85, 0xffff0000, v168
	v_lshlrev_b32_e32 v86, 16, v169
	v_and_b32_e32 v87, 0xffff0000, v169
	v_mul_f32_e32 v138, v10, v104
	v_mul_f32_e32 v139, v11, v105
	v_mul_f32_e32 v140, v12, v106
	v_mul_f32_e32 v141, v13, v107
	v_fma_f32 v66, v2, v66, v138
	v_fma_f32 v67, v3, v67, v139
	v_fma_f32 v68, v4, v68, v140
	v_fma_f32 v69, v5, v69, v141
	v_fma_f32 v66, v18, v120, v66
	v_fma_f32 v67, v19, v121, v67
	v_fma_f32 v68, v20, v122, v68
	v_fma_f32 v69, v21, v123, v69
	v_add_f32_e32 v66, v26, v66
	v_add_f32_e32 v67, v27, v67
	v_add_f32_e32 v68, v28, v68
	v_add_f32_e32 v69, v29, v69
	v_mul_f32_e32 v138, v14, v108
	v_mul_f32_e32 v139, v15, v109
	v_mul_f32_e32 v140, v16, v110
	v_mul_f32_e32 v141, v17, v111
	v_fma_f32 v70, v6, v70, v138
	v_fma_f32 v71, v7, v71, v139
	v_fma_f32 v72, v8, v72, v140
	v_fma_f32 v73, v9, v73, v141
	v_fma_f32 v70, v22, v124, v70
	v_fma_f32 v71, v23, v125, v71
	v_fma_f32 v72, v24, v126, v72
	v_fma_f32 v73, v25, v127, v73
	v_add_f32_e32 v70, v30, v70
	v_add_f32_e32 v71, v31, v71
	v_add_f32_e32 v72, v32, v72
	v_add_f32_e32 v73, v33, v73
	v_mul_f32_e32 v142, v42, v112
	v_mul_f32_e32 v143, v43, v113
	v_mul_f32_e32 v144, v44, v114
	v_mul_f32_e32 v145, v45, v115
	v_fma_f32 v74, v34, v74, v142
	v_fma_f32 v75, v35, v75, v143
	v_fma_f32 v76, v36, v76, v144
	v_fma_f32 v77, v37, v77, v145
	v_fma_f32 v74, v50, v128, v74
	v_fma_f32 v75, v51, v129, v75
	v_fma_f32 v76, v52, v82, v76
	v_fma_f32 v77, v53, v83, v77
	v_add_f32_e32 v74, v58, v74
	v_add_f32_e32 v75, v59, v75
	v_add_f32_e32 v76, v60, v76
	v_add_f32_e32 v77, v61, v77
	v_mul_f32_e32 v142, v46, v116
	v_mul_f32_e32 v143, v47, v117
	v_mul_f32_e32 v144, v48, v118
	v_mul_f32_e32 v145, v49, v119
	v_fma_f32 v78, v38, v78, v142
	v_fma_f32 v79, v39, v79, v143
	v_fma_f32 v80, v40, v80, v144
	v_fma_f32 v81, v41, v81, v145
	v_fma_f32 v78, v54, v84, v78
	v_fma_f32 v79, v55, v85, v79
	v_fma_f32 v80, v56, v86, v80
	v_fma_f32 v81, v57, v87, v81
	v_add_f32_e32 v78, v62, v78
	v_add_f32_e32 v79, v63, v79
	v_add_f32_e32 v80, v64, v80
	v_add_f32_e32 v81, v65, v81
	v_mul_f32_e32 v138, 0xbfb8aa3b, v74
	v_mul_f32_e32 v139, 0xbfb8aa3b, v75
	v_mul_f32_e32 v140, 0xbfb8aa3b, v76
	v_mul_f32_e32 v141, 0xbfb8aa3b, v77
	v_exp_f32_e32 v138, v138
	v_exp_f32_e32 v139, v139
	v_exp_f32_e32 v140, v140
	v_exp_f32_e32 v141, v141
	v_add_f32_e32 v138, 1.0, v138
	v_add_f32_e32 v139, 1.0, v139
	v_add_f32_e32 v140, 1.0, v140
	v_add_f32_e32 v141, 1.0, v141
	v_rcp_f32_e32 v138, v138
	v_rcp_f32_e32 v139, v139
	v_rcp_f32_e32 v140, v140
	v_rcp_f32_e32 v141, v141
	v_mul_f32_e32 v74, v74, v138
	v_mul_f32_e32 v75, v75, v139
	v_mul_f32_e32 v76, v76, v140
	v_mul_f32_e32 v77, v77, v141
	v_mul_f32_e32 v66, v66, v74
	v_mul_f32_e32 v67, v67, v75
	v_mul_f32_e32 v68, v68, v76
	v_mul_f32_e32 v69, v69, v77
	v_mul_f32_e32 v138, 0xbfb8aa3b, v78
	v_mul_f32_e32 v139, 0xbfb8aa3b, v79
	v_mul_f32_e32 v140, 0xbfb8aa3b, v80
	v_mul_f32_e32 v141, 0xbfb8aa3b, v81
	v_exp_f32_e32 v138, v138
	v_exp_f32_e32 v139, v139
	v_exp_f32_e32 v140, v140
	v_exp_f32_e32 v141, v141
	v_add_f32_e32 v138, 1.0, v138
	v_add_f32_e32 v139, 1.0, v139
	v_add_f32_e32 v140, 1.0, v140
	v_add_f32_e32 v141, 1.0, v141
	v_rcp_f32_e32 v138, v138
	v_rcp_f32_e32 v139, v139
	v_rcp_f32_e32 v140, v140
	v_rcp_f32_e32 v141, v141
	v_mul_f32_e32 v78, v78, v138
	v_mul_f32_e32 v79, v79, v139
	v_mul_f32_e32 v80, v80, v140
	v_mul_f32_e32 v81, v81, v141
	v_mul_f32_e32 v70, v70, v78
	v_mul_f32_e32 v71, v71, v79
	v_mul_f32_e32 v72, v72, v80
	v_mul_f32_e32 v73, v73, v81
	v_cvt_pk_bf16_f32 v100, v66, v67
	v_cvt_pk_bf16_f32 v101, v68, v69
	v_cvt_pk_bf16_f32 v102, v70, v71
	v_cvt_pk_bf16_f32 v103, v72, v73
	global_store_dwordx4 v[88:89], v[100:103], off nt
	v_lshl_add_u64 v[88:89], v[88:89], 0, s[10:11]
	s_waitcnt lgkmcnt(0)
	s_and_b64 s[28:29], exec, s[40:41]
	s_cbranch_scc0 .Lmy_e1_bot
	s_mov_b64 vcc, exec
	s_mov_b64 exec, s[28:29]
	v_mov_b32_e32 v170, 0
	v_mov_b32_e32 v171, 0
	v_mov_b32_e32 v172, 0
	v_mov_b32_e32 v173, 0
	v_mov_b32_e32 v174, 0
	v_mov_b32_e32 v175, 0
	v_mov_b32_e32 v176, 0
	v_mov_b32_e32 v177, 0
	s_mov_b64 exec, vcc
; #define GAS __attribute__((address_space(1)))
; DI unsigned pk2(float a, float b) { f32x2 v = {a, b}; bf2_t r = __builtin_convertvector(v, bf2_t); return __builtin_bit_cast(unsigned, r); }
; DI float bflo(unsigned w) { return __uint_as_float(w << 16); }
; DI float bfhi(unsigned w) { return __uint_as_float(w & 0xffff0000u); }
; DI float siluf(float v) { return v * __builtin_amdgcn_rcpf(1.f + __builtin_amdgcn_exp2f(-1.4426950408889634f * v)); }
;     ...
;         for (int q = 0; q < 4; ++q) {
;           const int hh = q >> 1, e0 = (q & 1) * 2;
;           const float ua0 = wa[0][hh][e0] * bflo(pa[q]) + wa[1][hh][e0] * bflo(ca[q]) + wa[2][hh][e0] * bflo(na[q]) + wa[3][hh][e0];
;           const float ua1 = wa[0][hh][e0 + 1] * bfhi(pa[q]) + wa[1][hh][e0 + 1] * bfhi(ca[q]) + wa[2][hh][e0 + 1] * bfhi(na[q]) + wa[3][hh][e0 + 1];
;           const float ug0 = wg[0][hh][e0] * bflo(pg[q]) + wg[1][hh][e0] * bflo(cg[q]) + wg[2][hh][e0] * bflo(ng[q]) + wg[3][hh][e0];
;           const float ug1 = wg[0][hh][e0 + 1] * bfhi(pg[q]) + wg[1][hh][e0 + 1] * bfhi(cg[q]) + wg[2][hh][e0 + 1] * bfhi(ng[q]) + wg[3][hh][e0 + 1];
;           resw[q] = pk2(siluf(ug0) * ua0, siluf(ug1) * ua1);
;         }
;         u32x4 w; w.x = resw[0]; w.y = resw[1]; w.z = resw[2]; w.w = resw[3];
;         __builtin_nontemporal_store(w, (GAS u32x4*)(ea.out + (size_t)(m0 + r) * 2816 + ja0 + j8));
.Lmy_e1_bot:
	v_lshlrev_b32_e32 v66, 16, v170
	v_and_b32_e32 v67, 0xffff0000, v170
	v_lshlrev_b32_e32 v68, 16, v171
	v_and_b32_e32 v69, 0xffff0000, v171
	v_lshlrev_b32_e32 v70, 16, v172
	v_and_b32_e32 v71, 0xffff0000, v172
	v_lshlrev_b32_e32 v72, 16, v173
	v_and_b32_e32 v73, 0xffff0000, v173
	v_lshlrev_b32_e32 v74, 16, v174
	v_and_b32_e32 v75, 0xffff0000, v174
	v_lshlrev_b32_e32 v76, 16, v175
	v_and_b32_e32 v77, 0xffff0000, v175
	v_lshlrev_b32_e32 v78, 16, v176
	v_and_b32_e32 v79, 0xffff0000, v176
	v_lshlrev_b32_e32 v80, 16, v177
	v_and_b32_e32 v81, 0xffff0000, v177
	v_mul_f32_e32 v138, v10, v120
	v_mul_f32_e32 v139, v11, v121
	v_mul_f32_e32 v140, v12, v122
	v_mul_f32_e32 v141, v13, v123
	v_fma_f32 v104, v2, v104, v138
	v_fma_f32 v105, v3, v105, v139
	v_fma_f32 v106, v4, v106, v140
	v_fma_f32 v107, v5, v107, v141
	v_fma_f32 v104, v18, v66, v104
	v_fma_f32 v105, v19, v67, v105
	v_fma_f32 v106, v20, v68, v106
	v_fma_f32 v107, v21, v69, v107
	v_add_f32_e32 v104, v26, v104
	v_add_f32_e32 v105, v27, v105
	v_add_f32_e32 v106, v28, v106
	v_add_f32_e32 v107, v29, v107
	v_mul_f32_e32 v138, v14, v124
	v_mul_f32_e32 v139, v15, v125
	v_mul_f32_e32 v140, v16, v126
	v_mul_f32_e32 v141, v17, v127
	v_fma_f32 v108, v6, v108, v138
	v_fma_f32 v109, v7, v109, v139
	v_fma_f32 v110, v8, v110, v140
	v_fma_f32 v111, v9, v111, v141
	v_fma_f32 v108, v22, v70, v108
	v_fma_f32 v109, v23, v71, v109
	v_fma_f32 v110, v24, v72, v110
	v_fma_f32 v111, v25, v73, v111
	v_add_f32_e32 v108, v30, v108
	v_add_f32_e32 v109, v31, v109
	v_add_f32_e32 v110, v32, v110
	v_add_f32_e32 v111, v33, v111
	v_mul_f32_e32 v142, v42, v128
	v_mul_f32_e32 v143, v43, v129
	v_mul_f32_e32 v144, v44, v82
	v_mul_f32_e32 v145, v45, v83
	v_fma_f32 v112, v34, v112, v142
	v_fma_f32 v113, v35, v113, v143
	v_fma_f32 v114, v36, v114, v144
	v_fma_f32 v115, v37, v115, v145
	v_fma_f32 v112, v50, v74, v112
	v_fma_f32 v113, v51, v75, v113
	v_fma_f32 v114, v52, v76, v114
	v_fma_f32 v115, v53, v77, v115
	v_add_f32_e32 v112, v58, v112
	v_add_f32_e32 v113, v59, v113
	v_add_f32_e32 v114, v60, v114
	v_add_f32_e32 v115, v61, v115
	v_mul_f32_e32 v142, v46, v84
	v_mul_f32_e32 v143, v47, v85
	v_mul_f32_e32 v144, v48, v86
	v_mul_f32_e32 v145, v49, v87
	v_fma_f32 v116, v38, v116, v142
	v_fma_f32 v117, v39, v117, v143
	v_fma_f32 v118, v40, v118, v144
	v_fma_f32 v119, v41, v119, v145
	v_fma_f32 v116, v54, v78, v116
	v_fma_f32 v117, v55, v79, v117
	v_fma_f32 v118, v56, v80, v118
	v_fma_f32 v119, v57, v81, v119
	v_add_f32_e32 v116, v62, v116
	v_add_f32_e32 v117, v63, v117
	v_add_f32_e32 v118, v64, v118
	v_add_f32_e32 v119, v65, v119
	v_mul_f32_e32 v138, 0xbfb8aa3b, v112
	v_mul_f32_e32 v139, 0xbfb8aa3b, v113
	v_mul_f32_e32 v140, 0xbfb8aa3b, v114
	v_mul_f32_e32 v141, 0xbfb8aa3b, v115
	v_exp_f32_e32 v138, v138
	v_exp_f32_e32 v139, v139
	v_exp_f32_e32 v140, v140
	v_exp_f32_e32 v141, v141
	v_add_f32_e32 v138, 1.0, v138
	v_add_f32_e32 v139, 1.0, v139
	v_add_f32_e32 v140, 1.0, v140
	v_add_f32_e32 v141, 1.0, v141
	v_rcp_f32_e32 v138, v138
	v_rcp_f32_e32 v139, v139
	v_rcp_f32_e32 v140, v140
	v_rcp_f32_e32 v141, v141
	v_mul_f32_e32 v112, v112, v138
	v_mul_f32_e32 v113, v113, v139
	v_mul_f32_e32 v114, v114, v140
	v_mul_f32_e32 v115, v115, v141
	v_mul_f32_e32 v104, v104, v112
	v_mul_f32_e32 v105, v105, v113
	v_mul_f32_e32 v106, v106, v114
	v_mul_f32_e32 v107, v107, v115
	v_mul_f32_e32 v138, 0xbfb8aa3b, v116
	v_mul_f32_e32 v139, 0xbfb8aa3b, v117
	v_mul_f32_e32 v140, 0xbfb8aa3b, v118
	v_mul_f32_e32 v141, 0xbfb8aa3b, v119
	v_exp_f32_e32 v138, v138
	v_exp_f32_e32 v139, v139
	v_exp_f32_e32 v140, v140
	v_exp_f32_e32 v141, v141
	v_add_f32_e32 v138, 1.0, v138
	v_add_f32_e32 v139, 1.0, v139
	v_add_f32_e32 v140, 1.0, v140
	v_add_f32_e32 v141, 1.0, v141
	v_rcp_f32_e32 v138, v138
	v_rcp_f32_e32 v139, v139
	v_rcp_f32_e32 v140, v140
	v_rcp_f32_e32 v141, v141
	v_mul_f32_e32 v116, v116, v138
	v_mul_f32_e32 v117, v117, v139
	v_mul_f32_e32 v118, v118, v140
	v_mul_f32_e32 v119, v119, v141
	v_mul_f32_e32 v108, v108, v116
	v_mul_f32_e32 v109, v109, v117
	v_mul_f32_e32 v110, v110, v118
	v_mul_f32_e32 v111, v111, v119
	v_cvt_pk_bf16_f32 v100, v104, v105
	v_cvt_pk_bf16_f32 v101, v106, v107
	v_cvt_pk_bf16_f32 v102, v108, v109
	v_cvt_pk_bf16_f32 v103, v110, v111
	s_mov_b64 vcc, exec
	s_orn2_b64 s[28:29], s[20:21], s[40:41]
	s_and_b64 exec, exec, s[28:29]
	global_store_dwordx4 v[88:89], v[100:103], off nt
	s_mov_b64 exec, vcc
	s_branch .LBB0_274
